# norm_rows<1> pass 2/3 with packed f32 math (v_pk_mul_f32 / v_pk_fma_f32, two partial sum-of-squares accumulators) on top of hand-written prologue converter
# speedup vs baseline: 1.0026x; 1.0026x over previous
; #define LAS __attribute__((address_space(3)))
; __device__ __forceinline__ void convert_segments(const Args& args, unsigned char* ws, LAS unsigned char* lds, int seg_lo, int seg_hi, int part_lo, int part_hi, int nparts, int wid, int nw, int wave, int lane) {
;     LAS float* scr = (LAS float*)(lds + wave * 16640);
; #pragma unroll 1
;     for (int sI = seg_lo; sI < seg_hi; ++sI) {
;         const Seg sg = seg_at(sI);
;         const int nblk = sg.ncols / 64, nit = (sg.K / 64) * nblk;
;         const float* W = args.in[sg.in_idx] + (size_t)sg.src_l * sg.K * sg.N;
;         bf16* WT = (bf16*)(ws + WS_W + (size_t)sg.layer * LAYER_W + (size_t)sg.wsub_mib * MiB);
;         const int it_lo = (int)((long)nit * part_lo / nparts), it_hi = (int)((long)nit * part_hi / nparts);
;         int it = it_lo + wid;
;         f32x4 v[16];
;         if (it < it_hi) { const int kb = it / nblk, nb = it - kb * nblk; tr_load(W + (size_t)(64 * kb) * sg.N + sg.scol + 64 * nb, sg.N, v, lane); }
cvp_done:
	s_waitcnt vmcnt(0) lgkmcnt(0)
	s_mov_b64 s[12:13], 0
	s_load_dwordx2 s[14:15], s[0:1], 0xe8
	s_mul_i32 s4, s89, 0x4100
	v_mbcnt_lo_u32_b32 v65, -1, 0
	v_mbcnt_hi_u32_b32 v65, -1, v65
	s_mov_b32 s21, 0
	v_lshlrev_b32_e32 v0, 3, v65
	s_waitcnt lgkmcnt(0)
	s_add_u32 s5, s14, s12
	s_addc_u32 s6, s15, s13
	s_cmpk_eq_i32 s88, 0x100
	s_cselect_b32 s19, 23, 26
	s_add_i32 s4, s4, 0
	s_add_u32 s24, s5, 0x2d400000
	v_ashrrev_i32_e32 v66, 4, v65
	v_lshlrev_b32_e32 v64, 2, v65
	s_movk_i32 s5, 0x104
	v_ashrrev_i32_e32 v102, 3, v65
	v_and_b32_e32 v0, 56, v0
	v_and_b32_e32 v68, 60, v64
	v_mul_lo_u32 v2, v66, s5
	v_mul_u32_u24_e32 v3, 0x104, v0
	v_lshlrev_b32_e32 v4, 2, v102
	v_readlane_b32 s5, v254, 0
	s_addc_u32 s25, s6, 0
	v_lshl_add_u32 v1, v68, 2, s4
	v_add3_u32 v67, s4, v3, v4
	s_lshl_b32 s27, s5, 9
	s_lshl_b32 s4, s89, 6
	s_add_i32 s27, s27, s4
	s_lshl_b32 s39, s5, 10
	s_lshl_b32 s4, s89, 7
	v_mov_b32_e32 v71, 0
	v_add_u32_e32 v72, 4, v66
	v_add_u32_e32 v74, 8, v66
	v_add_u32_e32 v76, 12, v66
	v_add_u32_e32 v78, 16, v66
	v_add_u32_e32 v80, 20, v66
	v_add_u32_e32 v82, 24, v66
	v_add_u32_e32 v84, 28, v66
	v_add_u32_e32 v86, 32, v66
	v_add_u32_e32 v88, 36, v66
	v_add_u32_e32 v90, 40, v66
	v_add_u32_e32 v92, 44, v66
	v_add_u32_e32 v94, 48, v66
	v_add_u32_e32 v96, 52, v66
	v_add_u32_e32 v98, 56, v66
	v_add_u32_e32 v100, 60, v66
	v_add_u32_e32 v104, 8, v102
	v_add_u32_e32 v106, 16, v102
	v_add_u32_e32 v108, 24, v102
	v_add_u32_e32 v110, 32, v102
	v_add_u32_e32 v112, 40, v102
	v_add_u32_e32 v114, 48, v102
	v_add_u32_e32 v116, 56, v102
	s_ashr_i32 s41, s40, 31
	s_abs_i32 s26, s40
	s_lshl_b32 s18, s88, 9
	s_add_i32 s39, s39, s4
	s_lshl_b32 s42, s88, 10
	v_add_u32_e32 v69, v1, v2
	v_lshlrev_b32_e32 v70, 1, v0
	s_mov_b32 s43, 0
	s_branch .LBB0_28

; #define LAS __attribute__((address_space(3)))
; __device__ __forceinline__ unsigned pk2(float lo, float hi) { const f32x2c v = {lo, hi}; return __builtin_bit_cast(unsigned, __builtin_convertvector(v, bf16x2c)); }
; __device__ __forceinline__ float bflo(unsigned w) { return __uint_as_float(w << 16); }
; __device__ __forceinline__ float bfhi(unsigned w) { return __uint_as_float(w & 0xffff0000u); }
; template <int MODE> ...
;     ...
;     for (int row = gw; row < SEQ; row += NGW) {
;     ...
;                 for (int j = 0; j < 16; ++j) { const f32x4 g = *(const LAS f32x4*)(GP + lo4 + 256 * j), gi = *(const LAS f32x4*)(GI + lo4 + 256 * j), gn = *(const LAS f32x4*)(GN + lo4 + 256 * j);
;                     f32x4 x;
;                     x.x = bflo(pw[j].x) * ri2 * gi.x + bflo(hw[j].x) * rstdb * g.x; x.y = bfhi(pw[j].x) * ri2 * gi.y + bfhi(hw[j].x) * rstdb * g.y;
;                     x.z = bflo(pw[j].y) * ri2 * gi.z + bflo(hw[j].y) * rstdb * g.z; x.w = bfhi(pw[j].y) * ri2 * gi.w + bfhi(hw[j].y) * rstdb * g.w;
;                     v2u w; w.x = pk2(x.x * rstd2 * gn.x, x.y * rstd2 * gn.y); w.y = pk2(x.z * rstd2 * gn.z, x.w * rstd2 * gn.w);
;                     *(v2u*)(pw_out + lo4 + 256 * j) = w;
;                     if (j & 1) __builtin_amdgcn_sched_barrier(0); }
.LBB0_775:
	s_or_b64 exec, exec, s[6:7]
	v_add_co_u32_e32 v224, vcc, s96, v66
	s_nop 1
	v_addc_co_u32_e32 v225, vcc, 0, v67, vcc
	v_add_co_u32_e32 v226, vcc, s97, v66
	s_nop 1
	v_addc_co_u32_e32 v227, vcc, 0, v67, vcc
	ds_read_b128 v[196:199], v71 offset:16384
	v_mov_b32_e32 v232, v70
	v_mov_b32_e32 v233, v70
	ds_read_b128 v[204:207], v71 offset:17408
	v_pk_mul_f32 v[212:213], v[232:233], v[132:133]
	v_pk_mul_f32 v[214:215], v[232:233], v[134:135]
	s_waitcnt lgkmcnt(1)
	v_pk_mul_f32 v[212:213], v[196:197], v[212:213]
	v_pk_mul_f32 v[214:215], v[198:199], v[214:215]
	v_cvt_pk_bf16_f32 v216, v212, v213
	v_cvt_pk_bf16_f32 v217, v214, v215
	global_store_dwordx2 v[224:225], v[216:217], off
	ds_read_b128 v[196:199], v71 offset:18432
	v_pk_mul_f32 v[212:213], v[232:233], v[136:137]
	v_pk_mul_f32 v[214:215], v[232:233], v[138:139]
	s_waitcnt lgkmcnt(1)
	v_pk_mul_f32 v[212:213], v[204:205], v[212:213]
	v_pk_mul_f32 v[214:215], v[206:207], v[214:215]
	v_cvt_pk_bf16_f32 v218, v212, v213
	v_cvt_pk_bf16_f32 v219, v214, v215
	global_store_dwordx2 v[224:225], v[218:219], off offset:512
	ds_read_b128 v[204:207], v71 offset:19456
	v_pk_mul_f32 v[212:213], v[232:233], v[140:141]
	v_pk_mul_f32 v[214:215], v[232:233], v[142:143]
	s_waitcnt lgkmcnt(1)
	v_pk_mul_f32 v[212:213], v[196:197], v[212:213]
	v_pk_mul_f32 v[214:215], v[198:199], v[214:215]
	v_cvt_pk_bf16_f32 v220, v212, v213
	v_cvt_pk_bf16_f32 v221, v214, v215
	global_store_dwordx2 v[224:225], v[220:221], off offset:1024
	ds_read_b128 v[196:199], v71 offset:20480
	v_pk_mul_f32 v[212:213], v[232:233], v[144:145]
	v_pk_mul_f32 v[214:215], v[232:233], v[146:147]
	s_waitcnt lgkmcnt(1)
	v_pk_mul_f32 v[212:213], v[204:205], v[212:213]
	v_pk_mul_f32 v[214:215], v[206:207], v[214:215]
	v_cvt_pk_bf16_f32 v222, v212, v213
	v_cvt_pk_bf16_f32 v223, v214, v215
	global_store_dwordx2 v[224:225], v[222:223], off offset:1536
	ds_read_b128 v[204:207], v71 offset:21504
	v_pk_mul_f32 v[212:213], v[232:233], v[148:149]
	v_pk_mul_f32 v[214:215], v[232:233], v[150:151]
	s_waitcnt lgkmcnt(1)
	v_pk_mul_f32 v[212:213], v[196:197], v[212:213]
	v_pk_mul_f32 v[214:215], v[198:199], v[214:215]
	v_cvt_pk_bf16_f32 v216, v212, v213
	v_cvt_pk_bf16_f32 v217, v214, v215
	global_store_dwordx2 v[224:225], v[216:217], off offset:2048
	ds_read_b128 v[196:199], v71 offset:22528
	v_pk_mul_f32 v[212:213], v[232:233], v[152:153]
	v_pk_mul_f32 v[214:215], v[232:233], v[154:155]
	s_waitcnt lgkmcnt(1)
	v_pk_mul_f32 v[212:213], v[204:205], v[212:213]
	v_pk_mul_f32 v[214:215], v[206:207], v[214:215]
	v_cvt_pk_bf16_f32 v218, v212, v213
	v_cvt_pk_bf16_f32 v219, v214, v215
	global_store_dwordx2 v[224:225], v[218:219], off offset:2560
	ds_read_b128 v[204:207], v71 offset:23552
	v_pk_mul_f32 v[212:213], v[232:233], v[156:157]
	v_pk_mul_f32 v[214:215], v[232:233], v[158:159]
	s_waitcnt lgkmcnt(1)
	v_pk_mul_f32 v[212:213], v[196:197], v[212:213]
	v_pk_mul_f32 v[214:215], v[198:199], v[214:215]
	v_cvt_pk_bf16_f32 v220, v212, v213
	v_cvt_pk_bf16_f32 v221, v214, v215
	global_store_dwordx2 v[224:225], v[220:221], off offset:3072
	ds_read_b128 v[196:199], v71 offset:24576
	v_pk_mul_f32 v[212:213], v[232:233], v[160:161]
	v_pk_mul_f32 v[214:215], v[232:233], v[162:163]
	s_waitcnt lgkmcnt(1)
	v_pk_mul_f32 v[212:213], v[204:205], v[212:213]
	v_pk_mul_f32 v[214:215], v[206:207], v[214:215]
	v_cvt_pk_bf16_f32 v222, v212, v213
	v_cvt_pk_bf16_f32 v223, v214, v215
	global_store_dwordx2 v[224:225], v[222:223], off offset:3584
	ds_read_b128 v[204:207], v71 offset:25600
	v_pk_mul_f32 v[212:213], v[232:233], v[164:165]
	v_pk_mul_f32 v[214:215], v[232:233], v[166:167]
	s_waitcnt lgkmcnt(1)
	v_pk_mul_f32 v[212:213], v[196:197], v[212:213]
	v_pk_mul_f32 v[214:215], v[198:199], v[214:215]
	v_cvt_pk_bf16_f32 v216, v212, v213
	v_cvt_pk_bf16_f32 v217, v214, v215
	global_store_dwordx2 v[226:227], v[216:217], off
	ds_read_b128 v[196:199], v71 offset:26624
	v_pk_mul_f32 v[212:213], v[232:233], v[168:169]
	v_pk_mul_f32 v[214:215], v[232:233], v[170:171]
	s_waitcnt lgkmcnt(1)
	v_pk_mul_f32 v[212:213], v[204:205], v[212:213]
	v_pk_mul_f32 v[214:215], v[206:207], v[214:215]
	v_cvt_pk_bf16_f32 v218, v212, v213
	v_cvt_pk_bf16_f32 v219, v214, v215
	global_store_dwordx2 v[226:227], v[218:219], off offset:512
	ds_read_b128 v[204:207], v71 offset:27648
	v_pk_mul_f32 v[212:213], v[232:233], v[172:173]
	v_pk_mul_f32 v[214:215], v[232:233], v[174:175]
	s_waitcnt lgkmcnt(1)
	v_pk_mul_f32 v[212:213], v[196:197], v[212:213]
	v_pk_mul_f32 v[214:215], v[198:199], v[214:215]
	v_cvt_pk_bf16_f32 v220, v212, v213
	v_cvt_pk_bf16_f32 v221, v214, v215
	global_store_dwordx2 v[226:227], v[220:221], off offset:1024
	ds_read_b128 v[196:199], v71 offset:28672
	v_pk_mul_f32 v[212:213], v[232:233], v[176:177]
	v_pk_mul_f32 v[214:215], v[232:233], v[178:179]
	s_waitcnt lgkmcnt(1)
	v_pk_mul_f32 v[212:213], v[204:205], v[212:213]
	v_pk_mul_f32 v[214:215], v[206:207], v[214:215]
	v_cvt_pk_bf16_f32 v222, v212, v213
	v_cvt_pk_bf16_f32 v223, v214, v215
	global_store_dwordx2 v[226:227], v[222:223], off offset:1536
	ds_read_b128 v[204:207], v71 offset:29696
	v_pk_mul_f32 v[212:213], v[232:233], v[180:181]
	v_pk_mul_f32 v[214:215], v[232:233], v[182:183]
	s_waitcnt lgkmcnt(1)
	v_pk_mul_f32 v[212:213], v[196:197], v[212:213]
	v_pk_mul_f32 v[214:215], v[198:199], v[214:215]
	v_cvt_pk_bf16_f32 v216, v212, v213
	v_cvt_pk_bf16_f32 v217, v214, v215
	global_store_dwordx2 v[226:227], v[216:217], off offset:2048
	ds_read_b128 v[196:199], v71 offset:30720
	v_pk_mul_f32 v[212:213], v[232:233], v[184:185]
	v_pk_mul_f32 v[214:215], v[232:233], v[186:187]
	s_waitcnt lgkmcnt(1)
	v_pk_mul_f32 v[212:213], v[204:205], v[212:213]
	v_pk_mul_f32 v[214:215], v[206:207], v[214:215]
	v_cvt_pk_bf16_f32 v218, v212, v213
	v_cvt_pk_bf16_f32 v219, v214, v215
	global_store_dwordx2 v[226:227], v[218:219], off offset:2560
	ds_read_b128 v[204:207], v71 offset:31744
	v_pk_mul_f32 v[212:213], v[232:233], v[188:189]
	v_pk_mul_f32 v[214:215], v[232:233], v[190:191]
	s_waitcnt lgkmcnt(1)
	v_pk_mul_f32 v[212:213], v[196:197], v[212:213]
	v_pk_mul_f32 v[214:215], v[198:199], v[214:215]
	v_cvt_pk_bf16_f32 v220, v212, v213
	v_cvt_pk_bf16_f32 v221, v214, v215
	global_store_dwordx2 v[226:227], v[220:221], off offset:3072
	v_pk_mul_f32 v[212:213], v[232:233], v[192:193]
	v_pk_mul_f32 v[214:215], v[232:233], v[194:195]
	s_waitcnt lgkmcnt(0)
	v_pk_mul_f32 v[212:213], v[204:205], v[212:213]
	v_pk_mul_f32 v[214:215], v[206:207], v[214:215]
	v_cvt_pk_bf16_f32 v222, v212, v213
	v_cvt_pk_bf16_f32 v223, v214, v215
	global_store_dwordx2 v[226:227], v[222:223], off offset:3584
	s_add_i32 s67, s67, s38
	s_add_u32 s64, s64, s8
	s_addc_u32 s65, s65, s9
	s_cmpk_lt_i32 s67, 0x2000
	v_lshl_add_u64 v[0:1], v[0:1], 0, s[10:11]
	s_cbranch_scc0 .LBB0_778
; __device__ __forceinline__ float bflo(unsigned w) { return __uint_as_float(w << 16); }
; __device__ __forceinline__ float bfhi(unsigned w) { return __uint_as_float(w & 0xffff0000u); }
; template <int MODE> ...
;     ...
;             const bf16* pr = xn + (size_t)row * DM; bf16* pw_out = xn_out + (size_t)row * DM; const bf16* hr = hb + (size_t)row * DM;
;             v2u pw[16], hw[16]; float ss = 0.f;
; #pragma unroll
;             for (int j = 0; j < 16; ++j) { pw[j] = *(const v2u*)(pr + lo4 + 256 * j); hw[j] = *(const v2u*)(hr + lo4 + 256 * j); }
;             const float ri = 1.f / rs[row];
; #pragma unroll
;             for (int j = 0; j < 16; ++j) { const float a = bflo(hw[j].x), b = bfhi(hw[j].x), c = bflo(hw[j].y), d = bfhi(hw[j].y); ss += a * a + b * b + c * c + d * d; }
.LBB0_776:
	v_lshl_add_u64 v[66:67], v[0:1], 0, s[12:13]
	v_add_co_u32_e32 v36, vcc, 0x3000000, v66
	s_mov_b64 s[6:7], vcc
	v_add_co_u32_e32 v2, vcc, 0x7000000, v66
	s_add_u32 s62, s64, s12
	s_nop 0
	v_addc_co_u32_e32 v3, vcc, 0, v67, vcc
	global_load_dwordx2 v[60:61], v[2:3], off
	global_load_dwordx2 v[54:55], v[2:3], off offset:512
	global_load_dwordx2 v[52:53], v[2:3], off offset:1024
	global_load_dwordx2 v[48:49], v[2:3], off offset:1536
	global_load_dwordx2 v[44:45], v[2:3], off offset:2048
	global_load_dwordx2 v[42:43], v[2:3], off offset:2560
	v_add_co_u32_e32 v4, vcc, s39, v66
	s_addc_u32 s63, s65, s13
	s_nop 0
	v_addc_co_u32_e32 v5, vcc, 0, v67, vcc
	v_add_co_u32_e32 v40, vcc, s41, v66
	s_waitcnt vmcnt(5)
	v_and_b32_e32 v69, 0xffff0000, v60
	v_addc_co_u32_e32 v41, vcc, 0, v67, vcc
	v_addc_co_u32_e64 v37, vcc, 0, v67, s[6:7]
	global_load_dwordx2 v[38:39], v[2:3], off offset:3072
	global_load_dwordx2 v[30:31], v[4:5], off
	global_load_dwordx2 v[26:27], v[4:5], off offset:512
	global_load_dwordx2 v[22:23], v[4:5], off offset:1024
	global_load_dwordx2 v[18:19], v[4:5], off offset:1536
	global_load_dwordx2 v[32:33], v[40:41], off
	global_load_dwordx2 v[28:29], v[40:41], off offset:512
	global_load_dwordx2 v[24:25], v[40:41], off offset:1024
	global_load_dwordx2 v[20:21], v[40:41], off offset:1536
	global_load_dwordx2 v[34:35], v[2:3], off offset:3584
	global_load_dwordx2 v[14:15], v[4:5], off offset:2048
	global_load_dwordx2 v[10:11], v[4:5], off offset:2560
	global_load_dwordx2 v[6:7], v[4:5], off offset:3072
	s_nop 0
	global_load_dwordx2 v[2:3], v[4:5], off offset:3584
	global_load_dwordx2 v[16:17], v[40:41], off offset:2048
	global_load_dwordx2 v[12:13], v[40:41], off offset:2560
	global_load_dwordx2 v[8:9], v[40:41], off offset:3072
	s_nop 0
	global_load_dwordx2 v[4:5], v[40:41], off offset:3584
	global_load_dword v78, v98, s[62:63]
	global_load_dwordx2 v[64:65], v[36:37], off
	global_load_dwordx2 v[62:63], v[36:37], off offset:512
	global_load_dwordx2 v[58:59], v[36:37], off offset:1024
	global_load_dwordx2 v[56:57], v[36:37], off offset:1536
	global_load_dwordx2 v[50:51], v[36:37], off offset:2048
	global_load_dwordx2 v[46:47], v[36:37], off offset:2560
	global_load_dwordx2 v[40:41], v[36:37], off offset:3072
	s_nop 0
	global_load_dwordx2 v[36:37], v[36:37], off offset:3584
	s_waitcnt vmcnt(31)
	v_and_b32_e32 v74, 0xffff0000, v54
	v_lshlrev_b32_e32 v68, 16, v60
	v_lshlrev_b32_e32 v73, 16, v54
	v_mul_f32_e32 v69, v69, v69
	v_mul_f32_e32 v74, v74, v74
	v_lshlrev_b32_e32 v70, 16, v61
	v_lshlrev_b32_e32 v75, 16, v55
	s_waitcnt vmcnt(30)
	v_and_b32_e32 v79, 0xffff0000, v52
	v_fmac_f32_e32 v69, v68, v68
	v_fmac_f32_e32 v74, v73, v73
	v_and_b32_e32 v72, 0xffff0000, v61
	v_and_b32_e32 v76, 0xffff0000, v55
	v_lshlrev_b32_e32 v77, 16, v52
	s_waitcnt vmcnt(29)
	v_and_b32_e32 v83, 0xffff0000, v48
	s_waitcnt vmcnt(28)
	v_and_b32_e32 v87, 0xffff0000, v44
	v_mul_f32_e32 v79, v79, v79
	v_fmac_f32_e32 v69, v70, v70
	v_fmac_f32_e32 v74, v75, v75
	v_lshlrev_b32_e32 v80, 16, v53
	v_lshlrev_b32_e32 v82, 16, v48
	v_lshlrev_b32_e32 v86, 16, v44
	v_mul_f32_e32 v83, v83, v83
	v_fmac_f32_e32 v79, v77, v77
	v_fmac_f32_e32 v69, v72, v72
	v_fmac_f32_e32 v74, v76, v76
	v_mul_f32_e32 v72, v87, v87
	v_and_b32_e32 v81, 0xffff0000, v53
	v_lshlrev_b32_e32 v84, 16, v49
	v_fmac_f32_e32 v83, v82, v82
	v_fmac_f32_e32 v79, v80, v80
	v_add_f32_e32 v68, v69, v74
	v_lshlrev_b32_e32 v69, 16, v45
	v_fmac_f32_e32 v72, v86, v86
	v_and_b32_e32 v85, 0xffff0000, v49
	v_fmac_f32_e32 v83, v84, v84
	v_fmac_f32_e32 v79, v81, v81
	v_and_b32_e32 v70, 0xffff0000, v45
	v_fmac_f32_e32 v72, v69, v69
	v_fmac_f32_e32 v83, v85, v85
	v_add_f32_e32 v68, v68, v79
	v_fmac_f32_e32 v72, v70, v70
	s_waitcnt vmcnt(27)
	v_and_b32_e32 v70, 0xffff0000, v42
	v_add_f32_e32 v68, v68, v83
	v_lshlrev_b32_e32 v69, 16, v42
	v_mul_f32_e32 v70, v70, v70
	v_add_f32_e32 v68, v68, v72
	v_lshlrev_b32_e32 v72, 16, v43
	v_fmac_f32_e32 v70, v69, v69
	v_and_b32_e32 v73, 0xffff0000, v43
	v_fmac_f32_e32 v70, v72, v72
	v_fmac_f32_e32 v70, v73, v73
	v_add_f32_e32 v68, v68, v70
	s_waitcnt vmcnt(26)
	v_and_b32_e32 v70, 0xffff0000, v38
	v_lshlrev_b32_e32 v69, 16, v38
	v_mul_f32_e32 v70, v70, v70
	v_lshlrev_b32_e32 v72, 16, v39
	v_fmac_f32_e32 v70, v69, v69
	v_and_b32_e32 v73, 0xffff0000, v39
	v_fmac_f32_e32 v70, v72, v72
	v_fmac_f32_e32 v70, v73, v73
	v_add_f32_e32 v68, v68, v70
	s_waitcnt vmcnt(17)
	v_and_b32_e32 v70, 0xffff0000, v34
	v_lshlrev_b32_e32 v69, 16, v34
	v_mul_f32_e32 v70, v70, v70
	v_lshlrev_b32_e32 v72, 16, v35
	v_fmac_f32_e32 v70, v69, v69
	v_and_b32_e32 v73, 0xffff0000, v35
	v_fmac_f32_e32 v70, v72, v72
	v_fmac_f32_e32 v70, v73, v73
	v_add_f32_e32 v68, v68, v70
	v_and_b32_e32 v70, 0xffff0000, v32
	v_lshlrev_b32_e32 v69, 16, v32
	v_mul_f32_e32 v70, v70, v70
	v_lshlrev_b32_e32 v72, 16, v33
	v_fmac_f32_e32 v70, v69, v69
	v_and_b32_e32 v73, 0xffff0000, v33
	v_fmac_f32_e32 v70, v72, v72
	v_fmac_f32_e32 v70, v73, v73
	v_add_f32_e32 v68, v68, v70
	v_and_b32_e32 v70, 0xffff0000, v28
	v_lshlrev_b32_e32 v69, 16, v28
	v_mul_f32_e32 v70, v70, v70
	v_lshlrev_b32_e32 v72, 16, v29
	v_fmac_f32_e32 v70, v69, v69
	v_and_b32_e32 v73, 0xffff0000, v29
	v_fmac_f32_e32 v70, v72, v72
	v_fmac_f32_e32 v70, v73, v73
	v_add_f32_e32 v68, v68, v70
	v_and_b32_e32 v70, 0xffff0000, v24
	v_lshlrev_b32_e32 v69, 16, v24
	v_mul_f32_e32 v70, v70, v70
	v_lshlrev_b32_e32 v72, 16, v25
	v_fmac_f32_e32 v70, v69, v69
	v_and_b32_e32 v73, 0xffff0000, v25
	v_fmac_f32_e32 v70, v72, v72
	v_fmac_f32_e32 v70, v73, v73
	v_add_f32_e32 v68, v68, v70
	v_and_b32_e32 v70, 0xffff0000, v20
	v_lshlrev_b32_e32 v69, 16, v20
	v_mul_f32_e32 v70, v70, v70
	v_lshlrev_b32_e32 v72, 16, v21
	v_fmac_f32_e32 v70, v69, v69
	v_and_b32_e32 v73, 0xffff0000, v21
	v_fmac_f32_e32 v70, v72, v72
	v_fmac_f32_e32 v70, v73, v73
	s_waitcnt vmcnt(11)
; #define LAS __attribute__((address_space(3)))
; __device__ __forceinline__ float bflo(unsigned w) { return __uint_as_float(w << 16); }
; __device__ __forceinline__ float bfhi(unsigned w) { return __uint_as_float(w & 0xffff0000u); }
; #define LAUNDER_ROW(pw, hw) do { LAUNDER8(pw, 0); LAUNDER8(pw, 8); LAUNDER8(hw, 0); LAUNDER8(hw, 8); } while (0)
; template <int MODE> ...
;     ...
;             const float ri = 1.f / rs[row];
; #pragma unroll
;             for (int j = 0; j < 16; ++j) { const float a = bflo(hw[j].x), b = bfhi(hw[j].x), c = bflo(hw[j].y), d = bfhi(hw[j].y); ss += a * a + b * b + c * c + d * d; }
;             const float rstd = rsqrtf(wave_sum(ss) * (1.f / DM) + EPS);
;             asm volatile("" ::: "memory");
;             LAUNDER_ROW(pw, hw);
;             float ss2 = 0.f;
; #pragma unroll
;             for (int j = 0; j < 16; ++j) { const f32x4 g = *(const LAS f32x4*)(GP + lo4 + 256 * j), gi = *(const LAS f32x4*)(GI + lo4 + 256 * j);
;                 f32x4 x;
;                 x.x = bflo(pw[j].x) * ri * gi.x + bflo(hw[j].x) * rstd * g.x; x.y = bfhi(pw[j].x) * ri * gi.y + bfhi(hw[j].x) * rstd * g.y;
;                 x.z = bflo(pw[j].y) * ri * gi.z + bflo(hw[j].y) * rstd * g.z; x.w = bfhi(pw[j].y) * ri * gi.w + bfhi(hw[j].y) * rstd * g.w;
;                 if (MODE == 2) *(f32x4*)(xout + (size_t)row * DM + lo4 + 256 * j) = x;
;                 else ss2 += x.x * x.x + x.y * x.y + x.z * x.z + x.w * x.w;
;                 if (j & 1) __builtin_amdgcn_sched_barrier(0); }
	v_and_b32_e32 v73, 0xffff0000, v12
	v_and_b32_e32 v72, 0xffff0000, v16
	v_add_f32_e32 v70, v68, v70
	v_lshlrev_b32_e32 v69, 16, v12
	v_lshlrev_b32_e32 v68, 16, v16
	v_pk_mul_f32 v[72:73], v[72:73], v[72:73]
	v_lshlrev_b32_e32 v75, 16, v13
	v_lshlrev_b32_e32 v74, 16, v17
	v_pk_fma_f32 v[68:69], v[68:69], v[68:69], v[72:73]
	v_and_b32_e32 v77, 0xffff0000, v13
	v_and_b32_e32 v76, 0xffff0000, v17
	v_pk_fma_f32 v[68:69], v[74:75], v[74:75], v[68:69]
	s_waitcnt vmcnt(9)
	v_and_b32_e32 v73, 0xffff0000, v4
	v_pk_fma_f32 v[68:69], v[76:77], v[76:77], v[68:69]
	v_and_b32_e32 v72, 0xffff0000, v8
	v_add_f32_e32 v68, v70, v68
	v_add_f32_e32 v70, v68, v69
	v_lshlrev_b32_e32 v69, 16, v4
	v_lshlrev_b32_e32 v68, 16, v8
	v_pk_mul_f32 v[72:73], v[72:73], v[72:73]
	v_lshlrev_b32_e32 v75, 16, v5
	v_lshlrev_b32_e32 v74, 16, v9
	v_pk_fma_f32 v[68:69], v[68:69], v[68:69], v[72:73]
	v_and_b32_e32 v77, 0xffff0000, v5
	v_and_b32_e32 v76, 0xffff0000, v9
	v_pk_fma_f32 v[68:69], v[74:75], v[74:75], v[68:69]
	s_waitcnt vmcnt(0)
	v_pk_fma_f32 v[68:69], v[76:77], v[76:77], v[68:69]
	v_div_scale_f32 v77, s[6:7], v78, v78, 1.0
	v_add_f32_e32 v68, v70, v68
	v_add_f32_e32 v68, v68, v69
	v_and_b32_e32 v69, 64, v100
	v_add_u32_e32 v69, 64, v69
	v_xor_b32_e32 v70, 1, v100
	v_cmp_lt_i32_e32 vcc, v70, v69
	v_rcp_f32_e32 v79, v77
	v_lshlrev_b32_e32 v86, 16, v60
	v_cndmask_b32_e32 v70, v100, v70, vcc
	v_lshlrev_b32_e32 v70, 2, v70
	ds_bpermute_b32 v72, v70, v68
	v_fma_f32 v80, -v77, v79, 1.0
	v_fmac_f32_e32 v79, v80, v79
	s_waitcnt lgkmcnt(0)
	v_add_f32_e32 v68, v68, v72
	v_xor_b32_e32 v72, 2, v100
	v_cmp_lt_i32_e32 vcc, v72, v69
	s_nop 1
	v_cndmask_b32_e32 v72, v100, v72, vcc
	v_lshlrev_b32_e32 v72, 2, v72
	ds_bpermute_b32 v73, v72, v68
	s_waitcnt lgkmcnt(0)
	v_add_f32_e32 v68, v68, v73
	v_xor_b32_e32 v73, 4, v100
	v_cmp_lt_i32_e32 vcc, v73, v69
	s_nop 1
	v_cndmask_b32_e32 v73, v100, v73, vcc
	v_lshlrev_b32_e32 v73, 2, v73
	ds_bpermute_b32 v74, v73, v68
	s_waitcnt lgkmcnt(0)
	v_add_f32_e32 v68, v68, v74
	v_xor_b32_e32 v74, 8, v100
	v_cmp_lt_i32_e32 vcc, v74, v69
	s_nop 1
	v_cndmask_b32_e32 v74, v100, v74, vcc
	v_lshlrev_b32_e32 v74, 2, v74
	ds_bpermute_b32 v75, v74, v68
	s_waitcnt lgkmcnt(0)
	v_add_f32_e32 v68, v68, v75
	v_xor_b32_e32 v75, 16, v100
	v_cmp_lt_i32_e32 vcc, v75, v69
	s_nop 1
	v_cndmask_b32_e32 v75, v100, v75, vcc
	v_lshlrev_b32_e32 v75, 2, v75
	ds_bpermute_b32 v76, v75, v68
	v_div_scale_f32 v80, vcc, 1.0, v78, 1.0
	v_mul_f32_e32 v81, v80, v79
	v_fma_f32 v82, -v77, v81, v80
	s_waitcnt lgkmcnt(0)
	v_add_f32_e32 v68, v68, v76
	v_xor_b32_e32 v76, 32, v100
	v_cmp_lt_i32_e64 s[6:7], v76, v69
	v_fmac_f32_e32 v81, v82, v79
	v_fma_f32 v77, -v77, v81, v80
	v_cndmask_b32_e64 v69, v100, v76, s[6:7]
	v_lshlrev_b32_e32 v76, 2, v69
	ds_bpermute_b32 v69, v76, v68
	s_waitcnt lgkmcnt(0)
	v_add_f32_e32 v68, v68, v69
	v_fmamk_f32 v68, v68, 0x39800000, v99
	v_mul_f32_e32 v69, 0x4b800000, v68
	v_cmp_gt_f32_e64 s[6:7], s66, v68
	s_nop 1
	v_cndmask_b32_e64 v68, v68, v69, s[6:7]
	v_rsq_f32_e32 v69, v68
	v_div_fmas_f32 v68, v77, v79, v81
	v_div_fixup_f32 v68, v68, v78, 1.0
	v_mul_f32_e32 v77, 0x45800000, v69
	v_cndmask_b32_e64 v69, v69, v77, s[6:7]
	v_mov_b32_e32 v228, v68
	v_mov_b32_e32 v229, v68
	v_mov_b32_e32 v230, v69
	v_mov_b32_e32 v231, v69
	ds_read_b128 v[196:199], v71
	ds_read_b128 v[200:203], v71 offset:32768
	ds_read_b128 v[204:207], v71 offset:1024
	ds_read_b128 v[208:211], v71 offset:33792
	v_lshlrev_b32_e32 v212, 16, v64
	v_and_b32_e32 v213, 0xffff0000, v64
	v_lshlrev_b32_e32 v214, 16, v65
	v_and_b32_e32 v215, 0xffff0000, v65
	v_lshlrev_b32_e32 v216, 16, v60
	v_and_b32_e32 v217, 0xffff0000, v60
	v_lshlrev_b32_e32 v218, 16, v61
	v_and_b32_e32 v219, 0xffff0000, v61
	v_pk_mul_f32 v[212:213], v[228:229], v[212:213]
	v_pk_mul_f32 v[214:215], v[228:229], v[214:215]
	v_pk_mul_f32 v[216:217], v[230:231], v[216:217]
	v_pk_mul_f32 v[218:219], v[230:231], v[218:219]
	s_waitcnt lgkmcnt(2)
	v_pk_mul_f32 v[132:133], v[212:213], v[200:201]
	v_pk_mul_f32 v[134:135], v[214:215], v[202:203]
	v_pk_fma_f32 v[132:133], v[196:197], v[216:217], v[132:133]
	v_pk_fma_f32 v[134:135], v[198:199], v[218:219], v[134:135]
	v_pk_mul_f32 v[234:235], v[132:133], v[132:133]
	v_pk_fma_f32 v[234:235], v[134:135], v[134:135], v[234:235]
	ds_read_b128 v[196:199], v71 offset:2048
	ds_read_b128 v[200:203], v71 offset:34816
	v_lshlrev_b32_e32 v212, 16, v62
	v_and_b32_e32 v213, 0xffff0000, v62
	v_lshlrev_b32_e32 v214, 16, v63
	v_and_b32_e32 v215, 0xffff0000, v63
	v_lshlrev_b32_e32 v216, 16, v54
	v_and_b32_e32 v217, 0xffff0000, v54
	v_lshlrev_b32_e32 v218, 16, v55
	v_and_b32_e32 v219, 0xffff0000, v55
	v_pk_mul_f32 v[212:213], v[228:229], v[212:213]
	v_pk_mul_f32 v[214:215], v[228:229], v[214:215]
	v_pk_mul_f32 v[216:217], v[230:231], v[216:217]
	v_pk_mul_f32 v[218:219], v[230:231], v[218:219]
	s_waitcnt lgkmcnt(2)
	v_pk_mul_f32 v[136:137], v[212:213], v[208:209]
	v_pk_mul_f32 v[138:139], v[214:215], v[210:211]
	v_pk_fma_f32 v[136:137], v[204:205], v[216:217], v[136:137]
	v_pk_fma_f32 v[138:139], v[206:207], v[218:219], v[138:139]
	v_pk_fma_f32 v[234:235], v[136:137], v[136:137], v[234:235]
	v_pk_fma_f32 v[234:235], v[138:139], v[138:139], v[234:235]
	ds_read_b128 v[204:207], v71 offset:3072
	ds_read_b128 v[208:211], v71 offset:35840
	v_lshlrev_b32_e32 v212, 16, v58
	v_and_b32_e32 v213, 0xffff0000, v58
	v_lshlrev_b32_e32 v214, 16, v59
	v_and_b32_e32 v215, 0xffff0000, v59
	v_lshlrev_b32_e32 v216, 16, v52
	v_and_b32_e32 v217, 0xffff0000, v52
	v_lshlrev_b32_e32 v218, 16, v53
	v_and_b32_e32 v219, 0xffff0000, v53
	v_pk_mul_f32 v[212:213], v[228:229], v[212:213]
	v_pk_mul_f32 v[214:215], v[228:229], v[214:215]
	v_pk_mul_f32 v[216:217], v[230:231], v[216:217]
	v_pk_mul_f32 v[218:219], v[230:231], v[218:219]
	s_waitcnt lgkmcnt(2)
; #define LAS __attribute__((address_space(3)))
; __device__ __forceinline__ float bflo(unsigned w) { return __uint_as_float(w << 16); }
; __device__ __forceinline__ float bfhi(unsigned w) { return __uint_as_float(w & 0xffff0000u); }
; template <int MODE> ...
;     ...
;             for (int j = 0; j < 16; ++j) { const f32x4 g = *(const LAS f32x4*)(GP + lo4 + 256 * j), gi = *(const LAS f32x4*)(GI + lo4 + 256 * j);
;                 f32x4 x;
;                 x.x = bflo(pw[j].x) * ri * gi.x + bflo(hw[j].x) * rstd * g.x; x.y = bfhi(pw[j].x) * ri * gi.y + bfhi(hw[j].x) * rstd * g.y;
;                 x.z = bflo(pw[j].y) * ri * gi.z + bflo(hw[j].y) * rstd * g.z; x.w = bfhi(pw[j].y) * ri * gi.w + bfhi(hw[j].y) * rstd * g.w;
;                 if (MODE == 2) *(f32x4*)(xout + (size_t)row * DM + lo4 + 256 * j) = x;
;                 else ss2 += x.x * x.x + x.y * x.y + x.z * x.z + x.w * x.w;
;                 if (j & 1) __builtin_amdgcn_sched_barrier(0); }
	v_pk_mul_f32 v[140:141], v[212:213], v[200:201]
	v_pk_mul_f32 v[142:143], v[214:215], v[202:203]
	v_pk_fma_f32 v[140:141], v[196:197], v[216:217], v[140:141]
	v_pk_fma_f32 v[142:143], v[198:199], v[218:219], v[142:143]
	v_pk_fma_f32 v[234:235], v[140:141], v[140:141], v[234:235]
	v_pk_fma_f32 v[234:235], v[142:143], v[142:143], v[234:235]
	ds_read_b128 v[196:199], v71 offset:4096
	ds_read_b128 v[200:203], v71 offset:36864
	v_lshlrev_b32_e32 v212, 16, v56
	v_and_b32_e32 v213, 0xffff0000, v56
	v_lshlrev_b32_e32 v214, 16, v57
	v_and_b32_e32 v215, 0xffff0000, v57
	v_lshlrev_b32_e32 v216, 16, v48
	v_and_b32_e32 v217, 0xffff0000, v48
	v_lshlrev_b32_e32 v218, 16, v49
	v_and_b32_e32 v219, 0xffff0000, v49
	v_pk_mul_f32 v[212:213], v[228:229], v[212:213]
	v_pk_mul_f32 v[214:215], v[228:229], v[214:215]
	v_pk_mul_f32 v[216:217], v[230:231], v[216:217]
	v_pk_mul_f32 v[218:219], v[230:231], v[218:219]
	s_waitcnt lgkmcnt(2)
	v_pk_mul_f32 v[144:145], v[212:213], v[208:209]
	v_pk_mul_f32 v[146:147], v[214:215], v[210:211]
	v_pk_fma_f32 v[144:145], v[204:205], v[216:217], v[144:145]
	v_pk_fma_f32 v[146:147], v[206:207], v[218:219], v[146:147]
	v_pk_fma_f32 v[234:235], v[144:145], v[144:145], v[234:235]
	v_pk_fma_f32 v[234:235], v[146:147], v[146:147], v[234:235]
	ds_read_b128 v[204:207], v71 offset:5120
	ds_read_b128 v[208:211], v71 offset:37888
	v_lshlrev_b32_e32 v212, 16, v50
	v_and_b32_e32 v213, 0xffff0000, v50
	v_lshlrev_b32_e32 v214, 16, v51
	v_and_b32_e32 v215, 0xffff0000, v51
	v_lshlrev_b32_e32 v216, 16, v44
	v_and_b32_e32 v217, 0xffff0000, v44
	v_lshlrev_b32_e32 v218, 16, v45
	v_and_b32_e32 v219, 0xffff0000, v45
	v_pk_mul_f32 v[212:213], v[228:229], v[212:213]
	v_pk_mul_f32 v[214:215], v[228:229], v[214:215]
	v_pk_mul_f32 v[216:217], v[230:231], v[216:217]
	v_pk_mul_f32 v[218:219], v[230:231], v[218:219]
	s_waitcnt lgkmcnt(2)
	v_pk_mul_f32 v[148:149], v[212:213], v[200:201]
	v_pk_mul_f32 v[150:151], v[214:215], v[202:203]
	v_pk_fma_f32 v[148:149], v[196:197], v[216:217], v[148:149]
	v_pk_fma_f32 v[150:151], v[198:199], v[218:219], v[150:151]
	v_pk_fma_f32 v[234:235], v[148:149], v[148:149], v[234:235]
	v_pk_fma_f32 v[234:235], v[150:151], v[150:151], v[234:235]
	ds_read_b128 v[196:199], v71 offset:6144
	ds_read_b128 v[200:203], v71 offset:38912
	v_lshlrev_b32_e32 v212, 16, v46
	v_and_b32_e32 v213, 0xffff0000, v46
	v_lshlrev_b32_e32 v214, 16, v47
	v_and_b32_e32 v215, 0xffff0000, v47
	v_lshlrev_b32_e32 v216, 16, v42
	v_and_b32_e32 v217, 0xffff0000, v42
	v_lshlrev_b32_e32 v218, 16, v43
	v_and_b32_e32 v219, 0xffff0000, v43
	v_pk_mul_f32 v[212:213], v[228:229], v[212:213]
	v_pk_mul_f32 v[214:215], v[228:229], v[214:215]
	v_pk_mul_f32 v[216:217], v[230:231], v[216:217]
	v_pk_mul_f32 v[218:219], v[230:231], v[218:219]
	s_waitcnt lgkmcnt(2)
	v_pk_mul_f32 v[152:153], v[212:213], v[208:209]
	v_pk_mul_f32 v[154:155], v[214:215], v[210:211]
	v_pk_fma_f32 v[152:153], v[204:205], v[216:217], v[152:153]
	v_pk_fma_f32 v[154:155], v[206:207], v[218:219], v[154:155]
	v_pk_fma_f32 v[234:235], v[152:153], v[152:153], v[234:235]
	v_pk_fma_f32 v[234:235], v[154:155], v[154:155], v[234:235]
	ds_read_b128 v[204:207], v71 offset:7168
	ds_read_b128 v[208:211], v71 offset:39936
	v_lshlrev_b32_e32 v212, 16, v40
	v_and_b32_e32 v213, 0xffff0000, v40
	v_lshlrev_b32_e32 v214, 16, v41
	v_and_b32_e32 v215, 0xffff0000, v41
	v_lshlrev_b32_e32 v216, 16, v38
	v_and_b32_e32 v217, 0xffff0000, v38
	v_lshlrev_b32_e32 v218, 16, v39
	v_and_b32_e32 v219, 0xffff0000, v39
	v_pk_mul_f32 v[212:213], v[228:229], v[212:213]
	v_pk_mul_f32 v[214:215], v[228:229], v[214:215]
	v_pk_mul_f32 v[216:217], v[230:231], v[216:217]
	v_pk_mul_f32 v[218:219], v[230:231], v[218:219]
	s_waitcnt lgkmcnt(2)
	v_pk_mul_f32 v[156:157], v[212:213], v[200:201]
	v_pk_mul_f32 v[158:159], v[214:215], v[202:203]
	v_pk_fma_f32 v[156:157], v[196:197], v[216:217], v[156:157]
	v_pk_fma_f32 v[158:159], v[198:199], v[218:219], v[158:159]
	v_pk_fma_f32 v[234:235], v[156:157], v[156:157], v[234:235]
	v_pk_fma_f32 v[234:235], v[158:159], v[158:159], v[234:235]
	ds_read_b128 v[196:199], v71 offset:8192
	ds_read_b128 v[200:203], v71 offset:40960
	v_lshlrev_b32_e32 v212, 16, v36
	v_and_b32_e32 v213, 0xffff0000, v36
	v_lshlrev_b32_e32 v214, 16, v37
	v_and_b32_e32 v215, 0xffff0000, v37
	v_lshlrev_b32_e32 v216, 16, v34
	v_and_b32_e32 v217, 0xffff0000, v34
	v_lshlrev_b32_e32 v218, 16, v35
	v_and_b32_e32 v219, 0xffff0000, v35
	v_pk_mul_f32 v[212:213], v[228:229], v[212:213]
	v_pk_mul_f32 v[214:215], v[228:229], v[214:215]
	v_pk_mul_f32 v[216:217], v[230:231], v[216:217]
	v_pk_mul_f32 v[218:219], v[230:231], v[218:219]
	s_waitcnt lgkmcnt(2)
	v_pk_mul_f32 v[160:161], v[212:213], v[208:209]
	v_pk_mul_f32 v[162:163], v[214:215], v[210:211]
	v_pk_fma_f32 v[160:161], v[204:205], v[216:217], v[160:161]
	v_pk_fma_f32 v[162:163], v[206:207], v[218:219], v[162:163]
	v_pk_fma_f32 v[234:235], v[160:161], v[160:161], v[234:235]
	v_pk_fma_f32 v[234:235], v[162:163], v[162:163], v[234:235]
	ds_read_b128 v[204:207], v71 offset:9216
	ds_read_b128 v[208:211], v71 offset:41984
	v_lshlrev_b32_e32 v212, 16, v30
	v_and_b32_e32 v213, 0xffff0000, v30
	v_lshlrev_b32_e32 v214, 16, v31
	v_and_b32_e32 v215, 0xffff0000, v31
	v_lshlrev_b32_e32 v216, 16, v32
	v_and_b32_e32 v217, 0xffff0000, v32
	v_lshlrev_b32_e32 v218, 16, v33
	v_and_b32_e32 v219, 0xffff0000, v33
	v_pk_mul_f32 v[212:213], v[228:229], v[212:213]
	v_pk_mul_f32 v[214:215], v[228:229], v[214:215]
	v_pk_mul_f32 v[216:217], v[230:231], v[216:217]
	v_pk_mul_f32 v[218:219], v[230:231], v[218:219]
	s_waitcnt lgkmcnt(2)
; #define LAS __attribute__((address_space(3)))
; __device__ __forceinline__ float bflo(unsigned w) { return __uint_as_float(w << 16); }
; __device__ __forceinline__ float bfhi(unsigned w) { return __uint_as_float(w & 0xffff0000u); }
; template <int MODE> ...
;     ...
;             for (int j = 0; j < 16; ++j) { const f32x4 g = *(const LAS f32x4*)(GP + lo4 + 256 * j), gi = *(const LAS f32x4*)(GI + lo4 + 256 * j);
;                 f32x4 x;
;                 x.x = bflo(pw[j].x) * ri * gi.x + bflo(hw[j].x) * rstd * g.x; x.y = bfhi(pw[j].x) * ri * gi.y + bfhi(hw[j].x) * rstd * g.y;
;                 x.z = bflo(pw[j].y) * ri * gi.z + bflo(hw[j].y) * rstd * g.z; x.w = bfhi(pw[j].y) * ri * gi.w + bfhi(hw[j].y) * rstd * g.w;
;                 if (MODE == 2) *(f32x4*)(xout + (size_t)row * DM + lo4 + 256 * j) = x;
;                 else ss2 += x.x * x.x + x.y * x.y + x.z * x.z + x.w * x.w;
;                 if (j & 1) __builtin_amdgcn_sched_barrier(0); }
	v_pk_mul_f32 v[164:165], v[212:213], v[200:201]
	v_pk_mul_f32 v[166:167], v[214:215], v[202:203]
	v_pk_fma_f32 v[164:165], v[196:197], v[216:217], v[164:165]
	v_pk_fma_f32 v[166:167], v[198:199], v[218:219], v[166:167]
	v_pk_fma_f32 v[234:235], v[164:165], v[164:165], v[234:235]
	v_pk_fma_f32 v[234:235], v[166:167], v[166:167], v[234:235]
	ds_read_b128 v[196:199], v71 offset:10240
	ds_read_b128 v[200:203], v71 offset:43008
	v_lshlrev_b32_e32 v212, 16, v26
	v_and_b32_e32 v213, 0xffff0000, v26
	v_lshlrev_b32_e32 v214, 16, v27
	v_and_b32_e32 v215, 0xffff0000, v27
	v_lshlrev_b32_e32 v216, 16, v28
	v_and_b32_e32 v217, 0xffff0000, v28
	v_lshlrev_b32_e32 v218, 16, v29
	v_and_b32_e32 v219, 0xffff0000, v29
	v_pk_mul_f32 v[212:213], v[228:229], v[212:213]
	v_pk_mul_f32 v[214:215], v[228:229], v[214:215]
	v_pk_mul_f32 v[216:217], v[230:231], v[216:217]
	v_pk_mul_f32 v[218:219], v[230:231], v[218:219]
	s_waitcnt lgkmcnt(2)
	v_pk_mul_f32 v[168:169], v[212:213], v[208:209]
	v_pk_mul_f32 v[170:171], v[214:215], v[210:211]
	v_pk_fma_f32 v[168:169], v[204:205], v[216:217], v[168:169]
	v_pk_fma_f32 v[170:171], v[206:207], v[218:219], v[170:171]
	v_pk_fma_f32 v[234:235], v[168:169], v[168:169], v[234:235]
	v_pk_fma_f32 v[234:235], v[170:171], v[170:171], v[234:235]
	ds_read_b128 v[204:207], v71 offset:11264
	ds_read_b128 v[208:211], v71 offset:44032
	v_lshlrev_b32_e32 v212, 16, v22
	v_and_b32_e32 v213, 0xffff0000, v22
	v_lshlrev_b32_e32 v214, 16, v23
	v_and_b32_e32 v215, 0xffff0000, v23
	v_lshlrev_b32_e32 v216, 16, v24
	v_and_b32_e32 v217, 0xffff0000, v24
	v_lshlrev_b32_e32 v218, 16, v25
	v_and_b32_e32 v219, 0xffff0000, v25
	v_pk_mul_f32 v[212:213], v[228:229], v[212:213]
	v_pk_mul_f32 v[214:215], v[228:229], v[214:215]
	v_pk_mul_f32 v[216:217], v[230:231], v[216:217]
	v_pk_mul_f32 v[218:219], v[230:231], v[218:219]
	s_waitcnt lgkmcnt(2)
	v_pk_mul_f32 v[172:173], v[212:213], v[200:201]
	v_pk_mul_f32 v[174:175], v[214:215], v[202:203]
	v_pk_fma_f32 v[172:173], v[196:197], v[216:217], v[172:173]
	v_pk_fma_f32 v[174:175], v[198:199], v[218:219], v[174:175]
	v_pk_fma_f32 v[234:235], v[172:173], v[172:173], v[234:235]
	v_pk_fma_f32 v[234:235], v[174:175], v[174:175], v[234:235]
	ds_read_b128 v[196:199], v71 offset:12288
	ds_read_b128 v[200:203], v71 offset:45056
	v_lshlrev_b32_e32 v212, 16, v18
	v_and_b32_e32 v213, 0xffff0000, v18
	v_lshlrev_b32_e32 v214, 16, v19
	v_and_b32_e32 v215, 0xffff0000, v19
	v_lshlrev_b32_e32 v216, 16, v20
	v_and_b32_e32 v217, 0xffff0000, v20
	v_lshlrev_b32_e32 v218, 16, v21
	v_and_b32_e32 v219, 0xffff0000, v21
	v_pk_mul_f32 v[212:213], v[228:229], v[212:213]
	v_pk_mul_f32 v[214:215], v[228:229], v[214:215]
	v_pk_mul_f32 v[216:217], v[230:231], v[216:217]
	v_pk_mul_f32 v[218:219], v[230:231], v[218:219]
	s_waitcnt lgkmcnt(2)
	v_pk_mul_f32 v[176:177], v[212:213], v[208:209]
	v_pk_mul_f32 v[178:179], v[214:215], v[210:211]
	v_pk_fma_f32 v[176:177], v[204:205], v[216:217], v[176:177]
	v_pk_fma_f32 v[178:179], v[206:207], v[218:219], v[178:179]
	v_pk_fma_f32 v[234:235], v[176:177], v[176:177], v[234:235]
	v_pk_fma_f32 v[234:235], v[178:179], v[178:179], v[234:235]
	ds_read_b128 v[204:207], v71 offset:13312
	ds_read_b128 v[208:211], v71 offset:46080
	v_lshlrev_b32_e32 v212, 16, v14
	v_and_b32_e32 v213, 0xffff0000, v14
	v_lshlrev_b32_e32 v214, 16, v15
	v_and_b32_e32 v215, 0xffff0000, v15
	v_lshlrev_b32_e32 v216, 16, v16
	v_and_b32_e32 v217, 0xffff0000, v16
	v_lshlrev_b32_e32 v218, 16, v17
	v_and_b32_e32 v219, 0xffff0000, v17
	v_pk_mul_f32 v[212:213], v[228:229], v[212:213]
	v_pk_mul_f32 v[214:215], v[228:229], v[214:215]
	v_pk_mul_f32 v[216:217], v[230:231], v[216:217]
	v_pk_mul_f32 v[218:219], v[230:231], v[218:219]
	s_waitcnt lgkmcnt(2)
; #define LAS __attribute__((address_space(3)))
; __device__ __forceinline__ float bflo(unsigned w) { return __uint_as_float(w << 16); }
; __device__ __forceinline__ float bfhi(unsigned w) { return __uint_as_float(w & 0xffff0000u); }
; template <int MODE> ...
;     ...
;             for (int j = 0; j < 16; ++j) { const f32x4 g = *(const LAS f32x4*)(GP + lo4 + 256 * j), gi = *(const LAS f32x4*)(GI + lo4 + 256 * j);
;                 f32x4 x;
;                 x.x = bflo(pw[j].x) * ri * gi.x + bflo(hw[j].x) * rstd * g.x; x.y = bfhi(pw[j].x) * ri * gi.y + bfhi(hw[j].x) * rstd * g.y;
;                 x.z = bflo(pw[j].y) * ri * gi.z + bflo(hw[j].y) * rstd * g.z; x.w = bfhi(pw[j].y) * ri * gi.w + bfhi(hw[j].y) * rstd * g.w;
;                 if (MODE == 2) *(f32x4*)(xout + (size_t)row * DM + lo4 + 256 * j) = x;
;                 else ss2 += x.x * x.x + x.y * x.y + x.z * x.z + x.w * x.w;
;                 if (j & 1) __builtin_amdgcn_sched_barrier(0); }
;             if (MODE == 1) {
;                 const float rstd2 = rsqrtf(wave_sum(ss2) * (1.f / DM) + EPS);
;                 if (lane == 0) rs_out[row] = rstd2;
	v_pk_mul_f32 v[180:181], v[212:213], v[200:201]
	v_pk_mul_f32 v[182:183], v[214:215], v[202:203]
	v_pk_fma_f32 v[180:181], v[196:197], v[216:217], v[180:181]
	v_pk_fma_f32 v[182:183], v[198:199], v[218:219], v[182:183]
	v_pk_fma_f32 v[234:235], v[180:181], v[180:181], v[234:235]
	v_pk_fma_f32 v[234:235], v[182:183], v[182:183], v[234:235]
	ds_read_b128 v[196:199], v71 offset:14336
	ds_read_b128 v[200:203], v71 offset:47104
	v_lshlrev_b32_e32 v212, 16, v10
	v_and_b32_e32 v213, 0xffff0000, v10
	v_lshlrev_b32_e32 v214, 16, v11
	v_and_b32_e32 v215, 0xffff0000, v11
	v_lshlrev_b32_e32 v216, 16, v12
	v_and_b32_e32 v217, 0xffff0000, v12
	v_lshlrev_b32_e32 v218, 16, v13
	v_and_b32_e32 v219, 0xffff0000, v13
	v_pk_mul_f32 v[212:213], v[228:229], v[212:213]
	v_pk_mul_f32 v[214:215], v[228:229], v[214:215]
	v_pk_mul_f32 v[216:217], v[230:231], v[216:217]
	v_pk_mul_f32 v[218:219], v[230:231], v[218:219]
	s_waitcnt lgkmcnt(2)
	v_pk_mul_f32 v[184:185], v[212:213], v[208:209]
	v_pk_mul_f32 v[186:187], v[214:215], v[210:211]
	v_pk_fma_f32 v[184:185], v[204:205], v[216:217], v[184:185]
	v_pk_fma_f32 v[186:187], v[206:207], v[218:219], v[186:187]
	v_pk_fma_f32 v[234:235], v[184:185], v[184:185], v[234:235]
	v_pk_fma_f32 v[234:235], v[186:187], v[186:187], v[234:235]
	ds_read_b128 v[204:207], v71 offset:15360
	ds_read_b128 v[208:211], v71 offset:48128
	v_lshlrev_b32_e32 v212, 16, v6
	v_and_b32_e32 v213, 0xffff0000, v6
	v_lshlrev_b32_e32 v214, 16, v7
	v_and_b32_e32 v215, 0xffff0000, v7
	v_lshlrev_b32_e32 v216, 16, v8
	v_and_b32_e32 v217, 0xffff0000, v8
	v_lshlrev_b32_e32 v218, 16, v9
	v_and_b32_e32 v219, 0xffff0000, v9
	v_pk_mul_f32 v[212:213], v[228:229], v[212:213]
	v_pk_mul_f32 v[214:215], v[228:229], v[214:215]
	v_pk_mul_f32 v[216:217], v[230:231], v[216:217]
	v_pk_mul_f32 v[218:219], v[230:231], v[218:219]
	s_waitcnt lgkmcnt(2)
	v_pk_mul_f32 v[188:189], v[212:213], v[200:201]
	v_pk_mul_f32 v[190:191], v[214:215], v[202:203]
	v_pk_fma_f32 v[188:189], v[196:197], v[216:217], v[188:189]
	v_pk_fma_f32 v[190:191], v[198:199], v[218:219], v[190:191]
	v_pk_fma_f32 v[234:235], v[188:189], v[188:189], v[234:235]
	v_pk_fma_f32 v[234:235], v[190:191], v[190:191], v[234:235]
	v_lshlrev_b32_e32 v212, 16, v2
	v_and_b32_e32 v213, 0xffff0000, v2
	v_lshlrev_b32_e32 v214, 16, v3
	v_and_b32_e32 v215, 0xffff0000, v3
	v_lshlrev_b32_e32 v216, 16, v4
	v_and_b32_e32 v217, 0xffff0000, v4
	v_lshlrev_b32_e32 v218, 16, v5
	v_and_b32_e32 v219, 0xffff0000, v5
	v_pk_mul_f32 v[212:213], v[228:229], v[212:213]
	v_pk_mul_f32 v[214:215], v[228:229], v[214:215]
	v_pk_mul_f32 v[216:217], v[230:231], v[216:217]
	v_pk_mul_f32 v[218:219], v[230:231], v[218:219]
	s_waitcnt lgkmcnt(0)
	v_pk_mul_f32 v[192:193], v[212:213], v[208:209]
	v_pk_mul_f32 v[194:195], v[214:215], v[210:211]
	v_pk_fma_f32 v[192:193], v[204:205], v[216:217], v[192:193]
	v_pk_fma_f32 v[194:195], v[206:207], v[218:219], v[194:195]
	v_pk_fma_f32 v[234:235], v[192:193], v[192:193], v[234:235]
	v_pk_fma_f32 v[234:235], v[194:195], v[194:195], v[234:235]
	v_add_f32_e32 v77, v234, v235
	ds_bpermute_b32 v70, v70, v77
	s_waitcnt lgkmcnt(0)
	v_add_f32_e32 v70, v77, v70
	ds_bpermute_b32 v72, v72, v70
	s_waitcnt lgkmcnt(0)
	v_add_f32_e32 v70, v70, v72
	ds_bpermute_b32 v72, v73, v70
	s_waitcnt lgkmcnt(0)
	v_add_f32_e32 v70, v70, v72
	ds_bpermute_b32 v72, v74, v70
	s_waitcnt lgkmcnt(0)
	v_add_f32_e32 v70, v70, v72
	ds_bpermute_b32 v72, v75, v70
	s_waitcnt lgkmcnt(0)
	v_add_f32_e32 v70, v70, v72
	ds_bpermute_b32 v72, v76, v70
	s_waitcnt lgkmcnt(0)
	v_add_f32_e32 v70, v70, v72
	v_fmamk_f32 v70, v70, 0x39800000, v99
	v_mul_f32_e32 v72, 0x4b800000, v70
	v_cmp_gt_f32_e32 vcc, s66, v70
	s_nop 1
	v_cndmask_b32_e32 v70, v70, v72, vcc
	v_rsq_f32_e32 v70, v70
	s_nop 0
	v_mul_f32_e32 v72, 0x45800000, v70
	v_cndmask_b32_e32 v70, v70, v72, vcc
	s_and_saveexec_b64 s[6:7], s[4:5]
	s_cbranch_execz .LBB0_775
	global_store_dword v98, v70, s[62:63]
	s_branch .LBB0_775

; #define LAS __attribute__((address_space(3)))
; __device__ __forceinline__ unsigned pk2(float lo, float hi) { const f32x2c v = {lo, hi}; return __builtin_bit_cast(unsigned, __builtin_convertvector(v, bf16x2c)); }
; __device__ __forceinline__ float bflo(unsigned w) { return __uint_as_float(w << 16); }
; __device__ __forceinline__ float bfhi(unsigned w) { return __uint_as_float(w & 0xffff0000u); }
; template <int MODE> ...
;     ...
;     for (int row = gw; row < SEQ; row += NGW) {
;     ...
;                 for (int j = 0; j < 16; ++j) { const f32x4 g = *(const LAS f32x4*)(GP + lo4 + 256 * j), gi = *(const LAS f32x4*)(GI + lo4 + 256 * j), gn = *(const LAS f32x4*)(GN + lo4 + 256 * j);
;                     f32x4 x;
;                     x.x = bflo(pw[j].x) * ri2 * gi.x + bflo(hw[j].x) * rstdb * g.x; x.y = bfhi(pw[j].x) * ri2 * gi.y + bfhi(hw[j].x) * rstdb * g.y;
;                     x.z = bflo(pw[j].y) * ri2 * gi.z + bflo(hw[j].y) * rstdb * g.z; x.w = bfhi(pw[j].y) * ri2 * gi.w + bfhi(hw[j].y) * rstdb * g.w;
;                     v2u w; w.x = pk2(x.x * rstd2 * gn.x, x.y * rstd2 * gn.y); w.y = pk2(x.z * rstd2 * gn.z, x.w * rstd2 * gn.w);
;                     *(v2u*)(pw_out + lo4 + 256 * j) = w;
;                     if (j & 1) __builtin_amdgcn_sched_barrier(0); }
.LBB0_1118:
	s_or_b64 exec, exec, s[6:7]
	v_mov_b32_e32 v78, v27
	v_add_co_u32_e32 v224, vcc, s96, v68
	s_nop 1
	v_addc_co_u32_e32 v225, vcc, 0, v69, vcc
	v_add_co_u32_e32 v226, vcc, s97, v68
	s_nop 1
	v_addc_co_u32_e32 v227, vcc, 0, v69, vcc
	ds_read_b128 v[196:199], v71 offset:16384
	v_mov_b32_e32 v232, v70
	v_mov_b32_e32 v233, v70
	ds_read_b128 v[204:207], v71 offset:17408
	v_pk_mul_f32 v[212:213], v[232:233], v[132:133]
	v_pk_mul_f32 v[214:215], v[232:233], v[134:135]
	s_waitcnt lgkmcnt(1)
	v_pk_mul_f32 v[212:213], v[196:197], v[212:213]
	v_pk_mul_f32 v[214:215], v[198:199], v[214:215]
	v_cvt_pk_bf16_f32 v216, v212, v213
	v_cvt_pk_bf16_f32 v217, v214, v215
	global_store_dwordx2 v[224:225], v[216:217], off
	ds_read_b128 v[196:199], v71 offset:18432
	v_pk_mul_f32 v[212:213], v[232:233], v[136:137]
	v_pk_mul_f32 v[214:215], v[232:233], v[138:139]
	s_waitcnt lgkmcnt(1)
	v_pk_mul_f32 v[212:213], v[204:205], v[212:213]
	v_pk_mul_f32 v[214:215], v[206:207], v[214:215]
	v_cvt_pk_bf16_f32 v218, v212, v213
	v_cvt_pk_bf16_f32 v219, v214, v215
	global_store_dwordx2 v[224:225], v[218:219], off offset:512
	ds_read_b128 v[204:207], v71 offset:19456
	v_pk_mul_f32 v[212:213], v[232:233], v[140:141]
	v_pk_mul_f32 v[214:215], v[232:233], v[142:143]
	s_waitcnt lgkmcnt(1)
	v_pk_mul_f32 v[212:213], v[196:197], v[212:213]
	v_pk_mul_f32 v[214:215], v[198:199], v[214:215]
	v_cvt_pk_bf16_f32 v220, v212, v213
	v_cvt_pk_bf16_f32 v221, v214, v215
	global_store_dwordx2 v[224:225], v[220:221], off offset:1024
	ds_read_b128 v[196:199], v71 offset:20480
	v_pk_mul_f32 v[212:213], v[232:233], v[144:145]
	v_pk_mul_f32 v[214:215], v[232:233], v[146:147]
	s_waitcnt lgkmcnt(1)
	v_pk_mul_f32 v[212:213], v[204:205], v[212:213]
	v_pk_mul_f32 v[214:215], v[206:207], v[214:215]
	v_cvt_pk_bf16_f32 v222, v212, v213
	v_cvt_pk_bf16_f32 v223, v214, v215
	global_store_dwordx2 v[224:225], v[222:223], off offset:1536
	ds_read_b128 v[204:207], v71 offset:21504
	v_pk_mul_f32 v[212:213], v[232:233], v[148:149]
	v_pk_mul_f32 v[214:215], v[232:233], v[150:151]
	s_waitcnt lgkmcnt(1)
	v_pk_mul_f32 v[212:213], v[196:197], v[212:213]
	v_pk_mul_f32 v[214:215], v[198:199], v[214:215]
	v_cvt_pk_bf16_f32 v216, v212, v213
	v_cvt_pk_bf16_f32 v217, v214, v215
	global_store_dwordx2 v[224:225], v[216:217], off offset:2048
	ds_read_b128 v[196:199], v71 offset:22528
	v_pk_mul_f32 v[212:213], v[232:233], v[152:153]
	v_pk_mul_f32 v[214:215], v[232:233], v[154:155]
	s_waitcnt lgkmcnt(1)
	v_pk_mul_f32 v[212:213], v[204:205], v[212:213]
	v_pk_mul_f32 v[214:215], v[206:207], v[214:215]
	v_cvt_pk_bf16_f32 v218, v212, v213
	v_cvt_pk_bf16_f32 v219, v214, v215
	global_store_dwordx2 v[224:225], v[218:219], off offset:2560
	ds_read_b128 v[204:207], v71 offset:23552
	v_pk_mul_f32 v[212:213], v[232:233], v[156:157]
	v_pk_mul_f32 v[214:215], v[232:233], v[158:159]
	s_waitcnt lgkmcnt(1)
	v_pk_mul_f32 v[212:213], v[196:197], v[212:213]
	v_pk_mul_f32 v[214:215], v[198:199], v[214:215]
	v_cvt_pk_bf16_f32 v220, v212, v213
	v_cvt_pk_bf16_f32 v221, v214, v215
	global_store_dwordx2 v[224:225], v[220:221], off offset:3072
	ds_read_b128 v[196:199], v71 offset:24576
	v_pk_mul_f32 v[212:213], v[232:233], v[160:161]
	v_pk_mul_f32 v[214:215], v[232:233], v[162:163]
	s_waitcnt lgkmcnt(1)
	v_pk_mul_f32 v[212:213], v[204:205], v[212:213]
	v_pk_mul_f32 v[214:215], v[206:207], v[214:215]
	v_cvt_pk_bf16_f32 v222, v212, v213
	v_cvt_pk_bf16_f32 v223, v214, v215
	global_store_dwordx2 v[224:225], v[222:223], off offset:3584
	ds_read_b128 v[204:207], v71 offset:25600
	v_pk_mul_f32 v[212:213], v[232:233], v[164:165]
	v_pk_mul_f32 v[214:215], v[232:233], v[166:167]
	s_waitcnt lgkmcnt(1)
	v_pk_mul_f32 v[212:213], v[196:197], v[212:213]
	v_pk_mul_f32 v[214:215], v[198:199], v[214:215]
	v_cvt_pk_bf16_f32 v216, v212, v213
	v_cvt_pk_bf16_f32 v217, v214, v215
	global_store_dwordx2 v[226:227], v[216:217], off
	ds_read_b128 v[196:199], v71 offset:26624
	v_pk_mul_f32 v[212:213], v[232:233], v[168:169]
	v_pk_mul_f32 v[214:215], v[232:233], v[170:171]
	s_waitcnt lgkmcnt(1)
	v_pk_mul_f32 v[212:213], v[204:205], v[212:213]
	v_pk_mul_f32 v[214:215], v[206:207], v[214:215]
	v_cvt_pk_bf16_f32 v218, v212, v213
	v_cvt_pk_bf16_f32 v219, v214, v215
	global_store_dwordx2 v[226:227], v[218:219], off offset:512
	ds_read_b128 v[204:207], v71 offset:27648
	v_pk_mul_f32 v[212:213], v[232:233], v[172:173]
	v_pk_mul_f32 v[214:215], v[232:233], v[174:175]
	s_waitcnt lgkmcnt(1)
	v_pk_mul_f32 v[212:213], v[196:197], v[212:213]
	v_pk_mul_f32 v[214:215], v[198:199], v[214:215]
	v_cvt_pk_bf16_f32 v220, v212, v213
	v_cvt_pk_bf16_f32 v221, v214, v215
	global_store_dwordx2 v[226:227], v[220:221], off offset:1024
	ds_read_b128 v[196:199], v71 offset:28672
	v_pk_mul_f32 v[212:213], v[232:233], v[176:177]
	v_pk_mul_f32 v[214:215], v[232:233], v[178:179]
	s_waitcnt lgkmcnt(1)
	v_pk_mul_f32 v[212:213], v[204:205], v[212:213]
	v_pk_mul_f32 v[214:215], v[206:207], v[214:215]
	v_cvt_pk_bf16_f32 v222, v212, v213
	v_cvt_pk_bf16_f32 v223, v214, v215
	global_store_dwordx2 v[226:227], v[222:223], off offset:1536
	ds_read_b128 v[204:207], v71 offset:29696
	v_pk_mul_f32 v[212:213], v[232:233], v[180:181]
	v_pk_mul_f32 v[214:215], v[232:233], v[182:183]
	s_waitcnt lgkmcnt(1)
	v_pk_mul_f32 v[212:213], v[196:197], v[212:213]
	v_pk_mul_f32 v[214:215], v[198:199], v[214:215]
	v_cvt_pk_bf16_f32 v216, v212, v213
	v_cvt_pk_bf16_f32 v217, v214, v215
	global_store_dwordx2 v[226:227], v[216:217], off offset:2048
	ds_read_b128 v[196:199], v71 offset:30720
	v_pk_mul_f32 v[212:213], v[232:233], v[184:185]
	v_pk_mul_f32 v[214:215], v[232:233], v[186:187]
	s_waitcnt lgkmcnt(1)
	v_pk_mul_f32 v[212:213], v[204:205], v[212:213]
	v_pk_mul_f32 v[214:215], v[206:207], v[214:215]
	v_cvt_pk_bf16_f32 v218, v212, v213
	v_cvt_pk_bf16_f32 v219, v214, v215
	global_store_dwordx2 v[226:227], v[218:219], off offset:2560
	ds_read_b128 v[204:207], v71 offset:31744
	v_pk_mul_f32 v[212:213], v[232:233], v[188:189]
	v_pk_mul_f32 v[214:215], v[232:233], v[190:191]
	s_waitcnt lgkmcnt(1)
	v_pk_mul_f32 v[212:213], v[196:197], v[212:213]
	v_pk_mul_f32 v[214:215], v[198:199], v[214:215]
	v_cvt_pk_bf16_f32 v220, v212, v213
	v_cvt_pk_bf16_f32 v221, v214, v215
	global_store_dwordx2 v[226:227], v[220:221], off offset:3072
	v_pk_mul_f32 v[212:213], v[232:233], v[192:193]
	v_pk_mul_f32 v[214:215], v[232:233], v[194:195]
	s_waitcnt lgkmcnt(0)
	v_pk_mul_f32 v[212:213], v[204:205], v[212:213]
	v_pk_mul_f32 v[214:215], v[206:207], v[214:215]
	v_cvt_pk_bf16_f32 v222, v212, v213
	v_cvt_pk_bf16_f32 v223, v214, v215
	global_store_dwordx2 v[226:227], v[222:223], off offset:3584
	s_add_i32 s67, s67, s38
	s_add_u32 s64, s64, s8
	s_addc_u32 s65, s65, s9
	s_cmpk_lt_i32 s67, 0x2000
	v_lshl_add_u64 v[0:1], v[0:1], 0, s[10:11]
	s_cbranch_scc0 .LBB0_1121
; __device__ __forceinline__ float bflo(unsigned w) { return __uint_as_float(w << 16); }
; __device__ __forceinline__ float bfhi(unsigned w) { return __uint_as_float(w & 0xffff0000u); }
; template <int MODE> ...
;     ...
;             const bf16* pr = xn + (size_t)row * DM; bf16* pw_out = xn_out + (size_t)row * DM; const bf16* hr = hb + (size_t)row * DM;
;             v2u pw[16], hw[16]; float ss = 0.f;
; #pragma unroll
;             for (int j = 0; j < 16; ++j) { pw[j] = *(const v2u*)(pr + lo4 + 256 * j); hw[j] = *(const v2u*)(hr + lo4 + 256 * j); }
;             const float ri = 1.f / rs[row];
; #pragma unroll
;             for (int j = 0; j < 16; ++j) { const float a = bflo(hw[j].x), b = bfhi(hw[j].x), c = bflo(hw[j].y), d = bfhi(hw[j].y); ss += a * a + b * b + c * c + d * d; }
.LBB0_1119:
	v_lshl_add_u64 v[68:69], v[0:1], 0, s[12:13]
	v_add_co_u32_e32 v26, vcc, 0x3000000, v68
	s_mov_b64 s[6:7], vcc
	v_add_co_u32_e32 v2, vcc, 0x7000000, v68
	s_add_u32 s62, s64, s12
	s_nop 0
	v_addc_co_u32_e32 v3, vcc, 0, v69, vcc
	global_load_dwordx2 v[60:61], v[2:3], off
	global_load_dwordx2 v[56:57], v[2:3], off offset:512
	global_load_dwordx2 v[54:55], v[2:3], off offset:1024
	global_load_dwordx2 v[50:51], v[2:3], off offset:1536
	global_load_dwordx2 v[46:47], v[2:3], off offset:2048
	global_load_dwordx2 v[44:45], v[2:3], off offset:2560
	v_add_co_u32_e32 v4, vcc, s39, v68
	s_addc_u32 s63, s65, s13
	s_nop 0
	v_addc_co_u32_e32 v5, vcc, 0, v69, vcc
	v_add_co_u32_e32 v38, vcc, s41, v68
	s_waitcnt vmcnt(5)
	v_lshlrev_b32_e32 v70, 16, v61
	v_addc_co_u32_e32 v39, vcc, 0, v69, vcc
	v_addc_co_u32_e64 v27, vcc, 0, v69, s[6:7]
	global_load_dwordx2 v[40:41], v[2:3], off offset:3072
	global_load_dwordx2 v[32:33], v[4:5], off
	global_load_dwordx2 v[28:29], v[4:5], off offset:512
	global_load_dwordx2 v[22:23], v[4:5], off offset:1024
	global_load_dwordx2 v[18:19], v[4:5], off offset:1536
	global_load_dwordx2 v[34:35], v[38:39], off
	global_load_dwordx2 v[30:31], v[38:39], off offset:512
	global_load_dwordx2 v[24:25], v[38:39], off offset:1024
	global_load_dwordx2 v[20:21], v[38:39], off offset:1536
	global_load_dwordx2 v[36:37], v[2:3], off offset:3584
	global_load_dwordx2 v[14:15], v[4:5], off offset:2048
	global_load_dwordx2 v[10:11], v[4:5], off offset:2560
	global_load_dwordx2 v[6:7], v[4:5], off offset:3072
	s_nop 0
	global_load_dwordx2 v[2:3], v[4:5], off offset:3584
	global_load_dwordx2 v[16:17], v[38:39], off offset:2048
	global_load_dwordx2 v[12:13], v[38:39], off offset:2560
	global_load_dwordx2 v[8:9], v[38:39], off offset:3072
	s_nop 0
	global_load_dwordx2 v[4:5], v[38:39], off offset:3584
	global_load_dword v78, v79, s[62:63]
	global_load_dwordx2 v[66:67], v[26:27], off
	global_load_dwordx2 v[64:65], v[26:27], off offset:512
	global_load_dwordx2 v[62:63], v[26:27], off offset:1024
	global_load_dwordx2 v[58:59], v[26:27], off offset:1536
	global_load_dwordx2 v[52:53], v[26:27], off offset:2048
	global_load_dwordx2 v[48:49], v[26:27], off offset:2560
	global_load_dwordx2 v[42:43], v[26:27], off offset:3072
	global_load_dwordx2 v[38:39], v[26:27], off offset:3584
	v_and_b32_e32 v27, 0xffff0000, v60
	s_waitcnt vmcnt(31)
	v_and_b32_e32 v74, 0xffff0000, v56
	v_lshlrev_b32_e32 v26, 16, v60
	v_lshlrev_b32_e32 v73, 16, v56
	v_mul_f32_e32 v27, v27, v27
	v_mul_f32_e32 v74, v74, v74
	v_lshlrev_b32_e32 v75, 16, v57
	s_waitcnt vmcnt(30)
	v_and_b32_e32 v80, 0xffff0000, v54
	v_fmac_f32_e32 v27, v26, v26
	v_fmac_f32_e32 v74, v73, v73
	v_and_b32_e32 v72, 0xffff0000, v61
	v_and_b32_e32 v76, 0xffff0000, v57
	v_lshlrev_b32_e32 v77, 16, v54
	s_waitcnt vmcnt(29)
	v_and_b32_e32 v84, 0xffff0000, v50
	s_waitcnt vmcnt(28)
	v_and_b32_e32 v88, 0xffff0000, v46
	v_mul_f32_e32 v80, v80, v80
	v_fmac_f32_e32 v27, v70, v70
	v_fmac_f32_e32 v74, v75, v75
	v_lshlrev_b32_e32 v81, 16, v55
	v_lshlrev_b32_e32 v83, 16, v50
	v_lshlrev_b32_e32 v87, 16, v46
	v_mul_f32_e32 v84, v84, v84
	v_fmac_f32_e32 v80, v77, v77
	v_fmac_f32_e32 v27, v72, v72
	v_fmac_f32_e32 v74, v76, v76
	v_mul_f32_e32 v72, v88, v88
	v_and_b32_e32 v82, 0xffff0000, v55
	v_lshlrev_b32_e32 v85, 16, v51
	v_fmac_f32_e32 v84, v83, v83
	v_fmac_f32_e32 v80, v81, v81
	v_add_f32_e32 v26, v27, v74
	v_lshlrev_b32_e32 v27, 16, v47
	v_fmac_f32_e32 v72, v87, v87
	v_and_b32_e32 v86, 0xffff0000, v51
	v_fmac_f32_e32 v84, v85, v85
	v_fmac_f32_e32 v80, v82, v82
	v_and_b32_e32 v70, 0xffff0000, v47
	v_fmac_f32_e32 v72, v27, v27
	v_fmac_f32_e32 v84, v86, v86
	v_add_f32_e32 v26, v26, v80
	v_fmac_f32_e32 v72, v70, v70
	s_waitcnt vmcnt(27)
	v_and_b32_e32 v70, 0xffff0000, v44
	v_add_f32_e32 v26, v26, v84
	v_lshlrev_b32_e32 v27, 16, v44
	v_mul_f32_e32 v70, v70, v70
	v_add_f32_e32 v26, v26, v72
	v_lshlrev_b32_e32 v72, 16, v45
	v_fmac_f32_e32 v70, v27, v27
	v_and_b32_e32 v73, 0xffff0000, v45
	v_fmac_f32_e32 v70, v72, v72
	v_fmac_f32_e32 v70, v73, v73
	v_add_f32_e32 v26, v26, v70
	s_waitcnt vmcnt(26)
	v_and_b32_e32 v70, 0xffff0000, v40
	v_lshlrev_b32_e32 v27, 16, v40
	v_mul_f32_e32 v70, v70, v70
	v_lshlrev_b32_e32 v72, 16, v41
	v_fmac_f32_e32 v70, v27, v27
	v_and_b32_e32 v73, 0xffff0000, v41
	v_fmac_f32_e32 v70, v72, v72
	v_fmac_f32_e32 v70, v73, v73
	v_add_f32_e32 v26, v26, v70
	s_waitcnt vmcnt(17)
	v_and_b32_e32 v70, 0xffff0000, v36
	v_lshlrev_b32_e32 v27, 16, v36
	v_mul_f32_e32 v70, v70, v70
	v_lshlrev_b32_e32 v72, 16, v37
	v_fmac_f32_e32 v70, v27, v27
	v_and_b32_e32 v73, 0xffff0000, v37
	v_fmac_f32_e32 v70, v72, v72
	v_fmac_f32_e32 v70, v73, v73
	v_add_f32_e32 v26, v26, v70
	v_and_b32_e32 v70, 0xffff0000, v34
	v_lshlrev_b32_e32 v27, 16, v34
	v_mul_f32_e32 v70, v70, v70
	v_lshlrev_b32_e32 v72, 16, v35
	v_fmac_f32_e32 v70, v27, v27
	v_and_b32_e32 v73, 0xffff0000, v35
	v_fmac_f32_e32 v70, v72, v72
	v_fmac_f32_e32 v70, v73, v73
	v_add_f32_e32 v26, v26, v70
	v_and_b32_e32 v70, 0xffff0000, v30
	v_lshlrev_b32_e32 v27, 16, v30
	v_mul_f32_e32 v70, v70, v70
	v_lshlrev_b32_e32 v72, 16, v31
	v_fmac_f32_e32 v70, v27, v27
	v_and_b32_e32 v73, 0xffff0000, v31
	v_fmac_f32_e32 v70, v72, v72
	v_fmac_f32_e32 v70, v73, v73
	v_add_f32_e32 v26, v26, v70
	v_and_b32_e32 v70, 0xffff0000, v24
	v_lshlrev_b32_e32 v27, 16, v24
	v_mul_f32_e32 v70, v70, v70
	v_lshlrev_b32_e32 v72, 16, v25
	v_fmac_f32_e32 v70, v27, v27
	v_and_b32_e32 v73, 0xffff0000, v25
	v_fmac_f32_e32 v70, v72, v72
	v_fmac_f32_e32 v70, v73, v73
	v_add_f32_e32 v26, v26, v70
	v_and_b32_e32 v70, 0xffff0000, v20
	v_lshlrev_b32_e32 v27, 16, v20
	v_mul_f32_e32 v70, v70, v70
	v_lshlrev_b32_e32 v72, 16, v21
	v_fmac_f32_e32 v70, v27, v27
	v_and_b32_e32 v73, 0xffff0000, v21
	v_fmac_f32_e32 v70, v72, v72
	v_fmac_f32_e32 v70, v73, v73
	s_waitcnt vmcnt(11)
; #define LAS __attribute__((address_space(3)))
; __device__ __forceinline__ float bflo(unsigned w) { return __uint_as_float(w << 16); }
; __device__ __forceinline__ float bfhi(unsigned w) { return __uint_as_float(w & 0xffff0000u); }
; #define LAUNDER_ROW(pw, hw) do { LAUNDER8(pw, 0); LAUNDER8(pw, 8); LAUNDER8(hw, 0); LAUNDER8(hw, 8); } while (0)
; template <int MODE> ...
;     ...
;             const float ri = 1.f / rs[row];
; #pragma unroll
;             for (int j = 0; j < 16; ++j) { const float a = bflo(hw[j].x), b = bfhi(hw[j].x), c = bflo(hw[j].y), d = bfhi(hw[j].y); ss += a * a + b * b + c * c + d * d; }
;             const float rstd = rsqrtf(wave_sum(ss) * (1.f / DM) + EPS);
;             asm volatile("" ::: "memory");
;             LAUNDER_ROW(pw, hw);
;             float ss2 = 0.f;
; #pragma unroll
;             for (int j = 0; j < 16; ++j) { const f32x4 g = *(const LAS f32x4*)(GP + lo4 + 256 * j), gi = *(const LAS f32x4*)(GI + lo4 + 256 * j);
;                 f32x4 x;
;                 x.x = bflo(pw[j].x) * ri * gi.x + bflo(hw[j].x) * rstd * g.x; x.y = bfhi(pw[j].x) * ri * gi.y + bfhi(hw[j].x) * rstd * g.y;
;                 x.z = bflo(pw[j].y) * ri * gi.z + bflo(hw[j].y) * rstd * g.z; x.w = bfhi(pw[j].y) * ri * gi.w + bfhi(hw[j].y) * rstd * g.w;
;                 if (MODE == 2) *(f32x4*)(xout + (size_t)row * DM + lo4 + 256 * j) = x;
;                 else ss2 += x.x * x.x + x.y * x.y + x.z * x.z + x.w * x.w;
;                 if (j & 1) __builtin_amdgcn_sched_barrier(0); }
	v_and_b32_e32 v73, 0xffff0000, v12
	v_and_b32_e32 v72, 0xffff0000, v16
	v_add_f32_e32 v70, v26, v70
	v_lshlrev_b32_e32 v27, 16, v12
	v_lshlrev_b32_e32 v26, 16, v16
	v_pk_mul_f32 v[72:73], v[72:73], v[72:73]
	v_lshlrev_b32_e32 v75, 16, v13
	v_lshlrev_b32_e32 v74, 16, v17
	v_pk_fma_f32 v[26:27], v[26:27], v[26:27], v[72:73]
	v_and_b32_e32 v77, 0xffff0000, v13
	v_and_b32_e32 v76, 0xffff0000, v17
	v_pk_fma_f32 v[26:27], v[74:75], v[74:75], v[26:27]
	s_waitcnt vmcnt(9)
	v_and_b32_e32 v73, 0xffff0000, v4
	v_pk_fma_f32 v[26:27], v[76:77], v[76:77], v[26:27]
	v_and_b32_e32 v72, 0xffff0000, v8
	v_add_f32_e32 v26, v70, v26
	v_add_f32_e32 v70, v26, v27
	v_lshlrev_b32_e32 v27, 16, v4
	v_lshlrev_b32_e32 v26, 16, v8
	v_pk_mul_f32 v[72:73], v[72:73], v[72:73]
	v_lshlrev_b32_e32 v75, 16, v5
	v_lshlrev_b32_e32 v74, 16, v9
	v_pk_fma_f32 v[26:27], v[26:27], v[26:27], v[72:73]
	v_and_b32_e32 v77, 0xffff0000, v5
	v_and_b32_e32 v76, 0xffff0000, v9
	v_pk_fma_f32 v[26:27], v[74:75], v[74:75], v[26:27]
	s_waitcnt vmcnt(0)
	v_pk_fma_f32 v[26:27], v[76:77], v[76:77], v[26:27]
	v_div_scale_f32 v77, s[6:7], v78, v78, 1.0
	v_add_f32_e32 v26, v70, v26
	v_add_f32_e32 v26, v26, v27
	v_and_b32_e32 v27, 64, v101
	v_add_u32_e32 v27, 64, v27
	v_xor_b32_e32 v70, 1, v101
	v_cmp_lt_i32_e32 vcc, v70, v27
	v_rcp_f32_e32 v80, v77
	s_nop 0
	v_cndmask_b32_e32 v70, v101, v70, vcc
	v_lshlrev_b32_e32 v70, 2, v70
	ds_bpermute_b32 v72, v70, v26
	v_fma_f32 v81, -v77, v80, 1.0
	v_fmac_f32_e32 v80, v81, v80
	s_waitcnt lgkmcnt(0)
	v_add_f32_e32 v26, v26, v72
	v_xor_b32_e32 v72, 2, v101
	v_cmp_lt_i32_e32 vcc, v72, v27
	s_nop 1
	v_cndmask_b32_e32 v72, v101, v72, vcc
	v_lshlrev_b32_e32 v72, 2, v72
	ds_bpermute_b32 v73, v72, v26
	s_waitcnt lgkmcnt(0)
	v_add_f32_e32 v26, v26, v73
	v_xor_b32_e32 v73, 4, v101
	v_cmp_lt_i32_e32 vcc, v73, v27
	s_nop 1
	v_cndmask_b32_e32 v73, v101, v73, vcc
	v_lshlrev_b32_e32 v73, 2, v73
	ds_bpermute_b32 v74, v73, v26
	s_waitcnt lgkmcnt(0)
	v_add_f32_e32 v26, v26, v74
	v_xor_b32_e32 v74, 8, v101
	v_cmp_lt_i32_e32 vcc, v74, v27
	s_nop 1
	v_cndmask_b32_e32 v74, v101, v74, vcc
	v_lshlrev_b32_e32 v74, 2, v74
	ds_bpermute_b32 v75, v74, v26
	s_waitcnt lgkmcnt(0)
	v_add_f32_e32 v26, v26, v75
	v_xor_b32_e32 v75, 16, v101
	v_cmp_lt_i32_e32 vcc, v75, v27
	s_nop 1
	v_cndmask_b32_e32 v75, v101, v75, vcc
	v_lshlrev_b32_e32 v75, 2, v75
	ds_bpermute_b32 v76, v75, v26
	v_div_scale_f32 v81, vcc, 1.0, v78, 1.0
	v_mul_f32_e32 v82, v81, v80
	v_fma_f32 v83, -v77, v82, v81
	s_waitcnt lgkmcnt(0)
	v_add_f32_e32 v26, v26, v76
	v_xor_b32_e32 v76, 32, v101
	v_cmp_lt_i32_e64 s[6:7], v76, v27
	v_fmac_f32_e32 v82, v83, v80
	v_fma_f32 v77, -v77, v82, v81
	v_cndmask_b32_e64 v27, v101, v76, s[6:7]
	v_lshlrev_b32_e32 v76, 2, v27
	ds_bpermute_b32 v27, v76, v26
	s_waitcnt lgkmcnt(0)
	v_add_f32_e32 v26, v26, v27
	v_fmamk_f32 v26, v26, 0x39800000, v100
	v_mul_f32_e32 v27, 0x4b800000, v26
	v_cmp_gt_f32_e64 s[6:7], s66, v26
	s_nop 1
	v_cndmask_b32_e64 v26, v26, v27, s[6:7]
	v_rsq_f32_e32 v27, v26
	v_div_fmas_f32 v26, v77, v80, v82
	v_div_fixup_f32 v26, v26, v78, 1.0
	v_mul_f32_e32 v77, 0x45800000, v27
	v_cndmask_b32_e64 v27, v27, v77, s[6:7]
	v_mov_b32_e32 v228, v26
	v_mov_b32_e32 v229, v26
	v_mov_b32_e32 v230, v27
	v_mov_b32_e32 v231, v27
	ds_read_b128 v[196:199], v71
	ds_read_b128 v[200:203], v71 offset:32768
	ds_read_b128 v[204:207], v71 offset:1024
	ds_read_b128 v[208:211], v71 offset:33792
	v_lshlrev_b32_e32 v212, 16, v66
	v_and_b32_e32 v213, 0xffff0000, v66
	v_lshlrev_b32_e32 v214, 16, v67
	v_and_b32_e32 v215, 0xffff0000, v67
	v_lshlrev_b32_e32 v216, 16, v60
	v_and_b32_e32 v217, 0xffff0000, v60
	v_lshlrev_b32_e32 v218, 16, v61
	v_and_b32_e32 v219, 0xffff0000, v61
	v_pk_mul_f32 v[212:213], v[228:229], v[212:213]
	v_pk_mul_f32 v[214:215], v[228:229], v[214:215]
	v_pk_mul_f32 v[216:217], v[230:231], v[216:217]
	v_pk_mul_f32 v[218:219], v[230:231], v[218:219]
	s_waitcnt lgkmcnt(2)
	v_pk_mul_f32 v[132:133], v[212:213], v[200:201]
	v_pk_mul_f32 v[134:135], v[214:215], v[202:203]
	v_pk_fma_f32 v[132:133], v[196:197], v[216:217], v[132:133]
	v_pk_fma_f32 v[134:135], v[198:199], v[218:219], v[134:135]
	v_pk_mul_f32 v[234:235], v[132:133], v[132:133]
	v_pk_fma_f32 v[234:235], v[134:135], v[134:135], v[234:235]
	ds_read_b128 v[196:199], v71 offset:2048
	ds_read_b128 v[200:203], v71 offset:34816
	v_lshlrev_b32_e32 v212, 16, v64
	v_and_b32_e32 v213, 0xffff0000, v64
	v_lshlrev_b32_e32 v214, 16, v65
	v_and_b32_e32 v215, 0xffff0000, v65
	v_lshlrev_b32_e32 v216, 16, v56
	v_and_b32_e32 v217, 0xffff0000, v56
	v_lshlrev_b32_e32 v218, 16, v57
	v_and_b32_e32 v219, 0xffff0000, v57
	v_pk_mul_f32 v[212:213], v[228:229], v[212:213]
	v_pk_mul_f32 v[214:215], v[228:229], v[214:215]
	v_pk_mul_f32 v[216:217], v[230:231], v[216:217]
	v_pk_mul_f32 v[218:219], v[230:231], v[218:219]
	s_waitcnt lgkmcnt(2)
	v_pk_mul_f32 v[136:137], v[212:213], v[208:209]
	v_pk_mul_f32 v[138:139], v[214:215], v[210:211]
	v_pk_fma_f32 v[136:137], v[204:205], v[216:217], v[136:137]
	v_pk_fma_f32 v[138:139], v[206:207], v[218:219], v[138:139]
	v_pk_fma_f32 v[234:235], v[136:137], v[136:137], v[234:235]
	v_pk_fma_f32 v[234:235], v[138:139], v[138:139], v[234:235]
	ds_read_b128 v[204:207], v71 offset:3072
	ds_read_b128 v[208:211], v71 offset:35840
	v_lshlrev_b32_e32 v212, 16, v62
	v_and_b32_e32 v213, 0xffff0000, v62
	v_lshlrev_b32_e32 v214, 16, v63
	v_and_b32_e32 v215, 0xffff0000, v63
	v_lshlrev_b32_e32 v216, 16, v54
	v_and_b32_e32 v217, 0xffff0000, v54
	v_lshlrev_b32_e32 v218, 16, v55
	v_and_b32_e32 v219, 0xffff0000, v55
	v_pk_mul_f32 v[212:213], v[228:229], v[212:213]
	v_pk_mul_f32 v[214:215], v[228:229], v[214:215]
	v_pk_mul_f32 v[216:217], v[230:231], v[216:217]
	v_pk_mul_f32 v[218:219], v[230:231], v[218:219]
	s_waitcnt lgkmcnt(2)
; #define LAS __attribute__((address_space(3)))
; __device__ __forceinline__ float bflo(unsigned w) { return __uint_as_float(w << 16); }
; __device__ __forceinline__ float bfhi(unsigned w) { return __uint_as_float(w & 0xffff0000u); }
; template <int MODE> ...
;     ...
;             for (int j = 0; j < 16; ++j) { const f32x4 g = *(const LAS f32x4*)(GP + lo4 + 256 * j), gi = *(const LAS f32x4*)(GI + lo4 + 256 * j);
;                 f32x4 x;
;                 x.x = bflo(pw[j].x) * ri * gi.x + bflo(hw[j].x) * rstd * g.x; x.y = bfhi(pw[j].x) * ri * gi.y + bfhi(hw[j].x) * rstd * g.y;
;                 x.z = bflo(pw[j].y) * ri * gi.z + bflo(hw[j].y) * rstd * g.z; x.w = bfhi(pw[j].y) * ri * gi.w + bfhi(hw[j].y) * rstd * g.w;
;                 if (MODE == 2) *(f32x4*)(xout + (size_t)row * DM + lo4 + 256 * j) = x;
;                 else ss2 += x.x * x.x + x.y * x.y + x.z * x.z + x.w * x.w;
;                 if (j & 1) __builtin_amdgcn_sched_barrier(0); }
	v_pk_mul_f32 v[140:141], v[212:213], v[200:201]
	v_pk_mul_f32 v[142:143], v[214:215], v[202:203]
	v_pk_fma_f32 v[140:141], v[196:197], v[216:217], v[140:141]
	v_pk_fma_f32 v[142:143], v[198:199], v[218:219], v[142:143]
	v_pk_fma_f32 v[234:235], v[140:141], v[140:141], v[234:235]
	v_pk_fma_f32 v[234:235], v[142:143], v[142:143], v[234:235]
	ds_read_b128 v[196:199], v71 offset:4096
	ds_read_b128 v[200:203], v71 offset:36864
	v_lshlrev_b32_e32 v212, 16, v58
	v_and_b32_e32 v213, 0xffff0000, v58
	v_lshlrev_b32_e32 v214, 16, v59
	v_and_b32_e32 v215, 0xffff0000, v59
	v_lshlrev_b32_e32 v216, 16, v50
	v_and_b32_e32 v217, 0xffff0000, v50
	v_lshlrev_b32_e32 v218, 16, v51
	v_and_b32_e32 v219, 0xffff0000, v51
	v_pk_mul_f32 v[212:213], v[228:229], v[212:213]
	v_pk_mul_f32 v[214:215], v[228:229], v[214:215]
	v_pk_mul_f32 v[216:217], v[230:231], v[216:217]
	v_pk_mul_f32 v[218:219], v[230:231], v[218:219]
	s_waitcnt lgkmcnt(2)
	v_pk_mul_f32 v[144:145], v[212:213], v[208:209]
	v_pk_mul_f32 v[146:147], v[214:215], v[210:211]
	v_pk_fma_f32 v[144:145], v[204:205], v[216:217], v[144:145]
	v_pk_fma_f32 v[146:147], v[206:207], v[218:219], v[146:147]
	v_pk_fma_f32 v[234:235], v[144:145], v[144:145], v[234:235]
	v_pk_fma_f32 v[234:235], v[146:147], v[146:147], v[234:235]
	ds_read_b128 v[204:207], v71 offset:5120
	ds_read_b128 v[208:211], v71 offset:37888
	v_lshlrev_b32_e32 v212, 16, v52
	v_and_b32_e32 v213, 0xffff0000, v52
	v_lshlrev_b32_e32 v214, 16, v53
	v_and_b32_e32 v215, 0xffff0000, v53
	v_lshlrev_b32_e32 v216, 16, v46
	v_and_b32_e32 v217, 0xffff0000, v46
	v_lshlrev_b32_e32 v218, 16, v47
	v_and_b32_e32 v219, 0xffff0000, v47
	v_pk_mul_f32 v[212:213], v[228:229], v[212:213]
	v_pk_mul_f32 v[214:215], v[228:229], v[214:215]
	v_pk_mul_f32 v[216:217], v[230:231], v[216:217]
	v_pk_mul_f32 v[218:219], v[230:231], v[218:219]
	s_waitcnt lgkmcnt(2)
	v_pk_mul_f32 v[148:149], v[212:213], v[200:201]
	v_pk_mul_f32 v[150:151], v[214:215], v[202:203]
	v_pk_fma_f32 v[148:149], v[196:197], v[216:217], v[148:149]
	v_pk_fma_f32 v[150:151], v[198:199], v[218:219], v[150:151]
	v_pk_fma_f32 v[234:235], v[148:149], v[148:149], v[234:235]
	v_pk_fma_f32 v[234:235], v[150:151], v[150:151], v[234:235]
	ds_read_b128 v[196:199], v71 offset:6144
	ds_read_b128 v[200:203], v71 offset:38912
	v_lshlrev_b32_e32 v212, 16, v48
	v_and_b32_e32 v213, 0xffff0000, v48
	v_lshlrev_b32_e32 v214, 16, v49
	v_and_b32_e32 v215, 0xffff0000, v49
	v_lshlrev_b32_e32 v216, 16, v44
	v_and_b32_e32 v217, 0xffff0000, v44
	v_lshlrev_b32_e32 v218, 16, v45
	v_and_b32_e32 v219, 0xffff0000, v45
	v_pk_mul_f32 v[212:213], v[228:229], v[212:213]
	v_pk_mul_f32 v[214:215], v[228:229], v[214:215]
	v_pk_mul_f32 v[216:217], v[230:231], v[216:217]
	v_pk_mul_f32 v[218:219], v[230:231], v[218:219]
	s_waitcnt lgkmcnt(2)
	v_pk_mul_f32 v[152:153], v[212:213], v[208:209]
	v_pk_mul_f32 v[154:155], v[214:215], v[210:211]
	v_pk_fma_f32 v[152:153], v[204:205], v[216:217], v[152:153]
	v_pk_fma_f32 v[154:155], v[206:207], v[218:219], v[154:155]
	v_pk_fma_f32 v[234:235], v[152:153], v[152:153], v[234:235]
	v_pk_fma_f32 v[234:235], v[154:155], v[154:155], v[234:235]
	ds_read_b128 v[204:207], v71 offset:7168
	ds_read_b128 v[208:211], v71 offset:39936
	v_lshlrev_b32_e32 v212, 16, v42
	v_and_b32_e32 v213, 0xffff0000, v42
	v_lshlrev_b32_e32 v214, 16, v43
	v_and_b32_e32 v215, 0xffff0000, v43
	v_lshlrev_b32_e32 v216, 16, v40
	v_and_b32_e32 v217, 0xffff0000, v40
	v_lshlrev_b32_e32 v218, 16, v41
	v_and_b32_e32 v219, 0xffff0000, v41
	v_pk_mul_f32 v[212:213], v[228:229], v[212:213]
	v_pk_mul_f32 v[214:215], v[228:229], v[214:215]
	v_pk_mul_f32 v[216:217], v[230:231], v[216:217]
	v_pk_mul_f32 v[218:219], v[230:231], v[218:219]
	s_waitcnt lgkmcnt(2)
	v_pk_mul_f32 v[156:157], v[212:213], v[200:201]
	v_pk_mul_f32 v[158:159], v[214:215], v[202:203]
	v_pk_fma_f32 v[156:157], v[196:197], v[216:217], v[156:157]
	v_pk_fma_f32 v[158:159], v[198:199], v[218:219], v[158:159]
	v_pk_fma_f32 v[234:235], v[156:157], v[156:157], v[234:235]
	v_pk_fma_f32 v[234:235], v[158:159], v[158:159], v[234:235]
	ds_read_b128 v[196:199], v71 offset:8192
	ds_read_b128 v[200:203], v71 offset:40960
	v_lshlrev_b32_e32 v212, 16, v38
	v_and_b32_e32 v213, 0xffff0000, v38
	v_lshlrev_b32_e32 v214, 16, v39
	v_and_b32_e32 v215, 0xffff0000, v39
	v_lshlrev_b32_e32 v216, 16, v36
	v_and_b32_e32 v217, 0xffff0000, v36
	v_lshlrev_b32_e32 v218, 16, v37
	v_and_b32_e32 v219, 0xffff0000, v37
	v_pk_mul_f32 v[212:213], v[228:229], v[212:213]
	v_pk_mul_f32 v[214:215], v[228:229], v[214:215]
	v_pk_mul_f32 v[216:217], v[230:231], v[216:217]
	v_pk_mul_f32 v[218:219], v[230:231], v[218:219]
	s_waitcnt lgkmcnt(2)
	v_pk_mul_f32 v[160:161], v[212:213], v[208:209]
	v_pk_mul_f32 v[162:163], v[214:215], v[210:211]
	v_pk_fma_f32 v[160:161], v[204:205], v[216:217], v[160:161]
	v_pk_fma_f32 v[162:163], v[206:207], v[218:219], v[162:163]
	v_pk_fma_f32 v[234:235], v[160:161], v[160:161], v[234:235]
	v_pk_fma_f32 v[234:235], v[162:163], v[162:163], v[234:235]
	ds_read_b128 v[204:207], v71 offset:9216
	ds_read_b128 v[208:211], v71 offset:41984
	v_lshlrev_b32_e32 v212, 16, v32
	v_and_b32_e32 v213, 0xffff0000, v32
	v_lshlrev_b32_e32 v214, 16, v33
	v_and_b32_e32 v215, 0xffff0000, v33
	v_lshlrev_b32_e32 v216, 16, v34
	v_and_b32_e32 v217, 0xffff0000, v34
	v_lshlrev_b32_e32 v218, 16, v35
	v_and_b32_e32 v219, 0xffff0000, v35
	v_pk_mul_f32 v[212:213], v[228:229], v[212:213]
	v_pk_mul_f32 v[214:215], v[228:229], v[214:215]
	v_pk_mul_f32 v[216:217], v[230:231], v[216:217]
	v_pk_mul_f32 v[218:219], v[230:231], v[218:219]
	s_waitcnt lgkmcnt(2)
; #define LAS __attribute__((address_space(3)))
; __device__ __forceinline__ float bflo(unsigned w) { return __uint_as_float(w << 16); }
; __device__ __forceinline__ float bfhi(unsigned w) { return __uint_as_float(w & 0xffff0000u); }
; template <int MODE> ...
;     ...
;             for (int j = 0; j < 16; ++j) { const f32x4 g = *(const LAS f32x4*)(GP + lo4 + 256 * j), gi = *(const LAS f32x4*)(GI + lo4 + 256 * j);
;                 f32x4 x;
;                 x.x = bflo(pw[j].x) * ri * gi.x + bflo(hw[j].x) * rstd * g.x; x.y = bfhi(pw[j].x) * ri * gi.y + bfhi(hw[j].x) * rstd * g.y;
;                 x.z = bflo(pw[j].y) * ri * gi.z + bflo(hw[j].y) * rstd * g.z; x.w = bfhi(pw[j].y) * ri * gi.w + bfhi(hw[j].y) * rstd * g.w;
;                 if (MODE == 2) *(f32x4*)(xout + (size_t)row * DM + lo4 + 256 * j) = x;
;                 else ss2 += x.x * x.x + x.y * x.y + x.z * x.z + x.w * x.w;
;                 if (j & 1) __builtin_amdgcn_sched_barrier(0); }
	v_pk_mul_f32 v[164:165], v[212:213], v[200:201]
	v_pk_mul_f32 v[166:167], v[214:215], v[202:203]
	v_pk_fma_f32 v[164:165], v[196:197], v[216:217], v[164:165]
	v_pk_fma_f32 v[166:167], v[198:199], v[218:219], v[166:167]
	v_pk_fma_f32 v[234:235], v[164:165], v[164:165], v[234:235]
	v_pk_fma_f32 v[234:235], v[166:167], v[166:167], v[234:235]
	ds_read_b128 v[196:199], v71 offset:10240
	ds_read_b128 v[200:203], v71 offset:43008
	v_lshlrev_b32_e32 v212, 16, v28
	v_and_b32_e32 v213, 0xffff0000, v28
	v_lshlrev_b32_e32 v214, 16, v29
	v_and_b32_e32 v215, 0xffff0000, v29
	v_lshlrev_b32_e32 v216, 16, v30
	v_and_b32_e32 v217, 0xffff0000, v30
	v_lshlrev_b32_e32 v218, 16, v31
	v_and_b32_e32 v219, 0xffff0000, v31
	v_pk_mul_f32 v[212:213], v[228:229], v[212:213]
	v_pk_mul_f32 v[214:215], v[228:229], v[214:215]
	v_pk_mul_f32 v[216:217], v[230:231], v[216:217]
	v_pk_mul_f32 v[218:219], v[230:231], v[218:219]
	s_waitcnt lgkmcnt(2)
	v_pk_mul_f32 v[168:169], v[212:213], v[208:209]
	v_pk_mul_f32 v[170:171], v[214:215], v[210:211]
	v_pk_fma_f32 v[168:169], v[204:205], v[216:217], v[168:169]
	v_pk_fma_f32 v[170:171], v[206:207], v[218:219], v[170:171]
	v_pk_fma_f32 v[234:235], v[168:169], v[168:169], v[234:235]
	v_pk_fma_f32 v[234:235], v[170:171], v[170:171], v[234:235]
	ds_read_b128 v[204:207], v71 offset:11264
	ds_read_b128 v[208:211], v71 offset:44032
	v_lshlrev_b32_e32 v212, 16, v22
	v_and_b32_e32 v213, 0xffff0000, v22
	v_lshlrev_b32_e32 v214, 16, v23
	v_and_b32_e32 v215, 0xffff0000, v23
	v_lshlrev_b32_e32 v216, 16, v24
	v_and_b32_e32 v217, 0xffff0000, v24
	v_lshlrev_b32_e32 v218, 16, v25
	v_and_b32_e32 v219, 0xffff0000, v25
	v_pk_mul_f32 v[212:213], v[228:229], v[212:213]
	v_pk_mul_f32 v[214:215], v[228:229], v[214:215]
	v_pk_mul_f32 v[216:217], v[230:231], v[216:217]
	v_pk_mul_f32 v[218:219], v[230:231], v[218:219]
	s_waitcnt lgkmcnt(2)
	v_pk_mul_f32 v[172:173], v[212:213], v[200:201]
	v_pk_mul_f32 v[174:175], v[214:215], v[202:203]
	v_pk_fma_f32 v[172:173], v[196:197], v[216:217], v[172:173]
	v_pk_fma_f32 v[174:175], v[198:199], v[218:219], v[174:175]
	v_pk_fma_f32 v[234:235], v[172:173], v[172:173], v[234:235]
	v_pk_fma_f32 v[234:235], v[174:175], v[174:175], v[234:235]
	ds_read_b128 v[196:199], v71 offset:12288
	ds_read_b128 v[200:203], v71 offset:45056
	v_lshlrev_b32_e32 v212, 16, v18
	v_and_b32_e32 v213, 0xffff0000, v18
	v_lshlrev_b32_e32 v214, 16, v19
	v_and_b32_e32 v215, 0xffff0000, v19
	v_lshlrev_b32_e32 v216, 16, v20
	v_and_b32_e32 v217, 0xffff0000, v20
	v_lshlrev_b32_e32 v218, 16, v21
	v_and_b32_e32 v219, 0xffff0000, v21
	v_pk_mul_f32 v[212:213], v[228:229], v[212:213]
	v_pk_mul_f32 v[214:215], v[228:229], v[214:215]
	v_pk_mul_f32 v[216:217], v[230:231], v[216:217]
	v_pk_mul_f32 v[218:219], v[230:231], v[218:219]
	s_waitcnt lgkmcnt(2)
	v_pk_mul_f32 v[176:177], v[212:213], v[208:209]
	v_pk_mul_f32 v[178:179], v[214:215], v[210:211]
	v_pk_fma_f32 v[176:177], v[204:205], v[216:217], v[176:177]
	v_pk_fma_f32 v[178:179], v[206:207], v[218:219], v[178:179]
	v_pk_fma_f32 v[234:235], v[176:177], v[176:177], v[234:235]
	v_pk_fma_f32 v[234:235], v[178:179], v[178:179], v[234:235]
	ds_read_b128 v[204:207], v71 offset:13312
	ds_read_b128 v[208:211], v71 offset:46080
	v_lshlrev_b32_e32 v212, 16, v14
	v_and_b32_e32 v213, 0xffff0000, v14
	v_lshlrev_b32_e32 v214, 16, v15
	v_and_b32_e32 v215, 0xffff0000, v15
	v_lshlrev_b32_e32 v216, 16, v16
	v_and_b32_e32 v217, 0xffff0000, v16
	v_lshlrev_b32_e32 v218, 16, v17
	v_and_b32_e32 v219, 0xffff0000, v17
	v_pk_mul_f32 v[212:213], v[228:229], v[212:213]
	v_pk_mul_f32 v[214:215], v[228:229], v[214:215]
	v_pk_mul_f32 v[216:217], v[230:231], v[216:217]
	v_pk_mul_f32 v[218:219], v[230:231], v[218:219]
	s_waitcnt lgkmcnt(2)
; #define LAS __attribute__((address_space(3)))
; __device__ __forceinline__ float bflo(unsigned w) { return __uint_as_float(w << 16); }
; __device__ __forceinline__ float bfhi(unsigned w) { return __uint_as_float(w & 0xffff0000u); }
; template <int MODE> ...
;     ...
;             for (int j = 0; j < 16; ++j) { const f32x4 g = *(const LAS f32x4*)(GP + lo4 + 256 * j), gi = *(const LAS f32x4*)(GI + lo4 + 256 * j);
;                 f32x4 x;
;                 x.x = bflo(pw[j].x) * ri * gi.x + bflo(hw[j].x) * rstd * g.x; x.y = bfhi(pw[j].x) * ri * gi.y + bfhi(hw[j].x) * rstd * g.y;
;                 x.z = bflo(pw[j].y) * ri * gi.z + bflo(hw[j].y) * rstd * g.z; x.w = bfhi(pw[j].y) * ri * gi.w + bfhi(hw[j].y) * rstd * g.w;
;                 if (MODE == 2) *(f32x4*)(xout + (size_t)row * DM + lo4 + 256 * j) = x;
;                 else ss2 += x.x * x.x + x.y * x.y + x.z * x.z + x.w * x.w;
;                 if (j & 1) __builtin_amdgcn_sched_barrier(0); }
;             if (MODE == 1) {
;                 const float rstd2 = rsqrtf(wave_sum(ss2) * (1.f / DM) + EPS);
;                 if (lane == 0) rs_out[row] = rstd2;
	v_pk_mul_f32 v[180:181], v[212:213], v[200:201]
	v_pk_mul_f32 v[182:183], v[214:215], v[202:203]
	v_pk_fma_f32 v[180:181], v[196:197], v[216:217], v[180:181]
	v_pk_fma_f32 v[182:183], v[198:199], v[218:219], v[182:183]
	v_pk_fma_f32 v[234:235], v[180:181], v[180:181], v[234:235]
	v_pk_fma_f32 v[234:235], v[182:183], v[182:183], v[234:235]
	ds_read_b128 v[196:199], v71 offset:14336
	ds_read_b128 v[200:203], v71 offset:47104
	v_lshlrev_b32_e32 v212, 16, v10
	v_and_b32_e32 v213, 0xffff0000, v10
	v_lshlrev_b32_e32 v214, 16, v11
	v_and_b32_e32 v215, 0xffff0000, v11
	v_lshlrev_b32_e32 v216, 16, v12
	v_and_b32_e32 v217, 0xffff0000, v12
	v_lshlrev_b32_e32 v218, 16, v13
	v_and_b32_e32 v219, 0xffff0000, v13
	v_pk_mul_f32 v[212:213], v[228:229], v[212:213]
	v_pk_mul_f32 v[214:215], v[228:229], v[214:215]
	v_pk_mul_f32 v[216:217], v[230:231], v[216:217]
	v_pk_mul_f32 v[218:219], v[230:231], v[218:219]
	s_waitcnt lgkmcnt(2)
	v_pk_mul_f32 v[184:185], v[212:213], v[208:209]
	v_pk_mul_f32 v[186:187], v[214:215], v[210:211]
	v_pk_fma_f32 v[184:185], v[204:205], v[216:217], v[184:185]
	v_pk_fma_f32 v[186:187], v[206:207], v[218:219], v[186:187]
	v_pk_fma_f32 v[234:235], v[184:185], v[184:185], v[234:235]
	v_pk_fma_f32 v[234:235], v[186:187], v[186:187], v[234:235]
	ds_read_b128 v[204:207], v71 offset:15360
	ds_read_b128 v[208:211], v71 offset:48128
	v_lshlrev_b32_e32 v212, 16, v6
	v_and_b32_e32 v213, 0xffff0000, v6
	v_lshlrev_b32_e32 v214, 16, v7
	v_and_b32_e32 v215, 0xffff0000, v7
	v_lshlrev_b32_e32 v216, 16, v8
	v_and_b32_e32 v217, 0xffff0000, v8
	v_lshlrev_b32_e32 v218, 16, v9
	v_and_b32_e32 v219, 0xffff0000, v9
	v_pk_mul_f32 v[212:213], v[228:229], v[212:213]
	v_pk_mul_f32 v[214:215], v[228:229], v[214:215]
	v_pk_mul_f32 v[216:217], v[230:231], v[216:217]
	v_pk_mul_f32 v[218:219], v[230:231], v[218:219]
	s_waitcnt lgkmcnt(2)
	v_pk_mul_f32 v[188:189], v[212:213], v[200:201]
	v_pk_mul_f32 v[190:191], v[214:215], v[202:203]
	v_pk_fma_f32 v[188:189], v[196:197], v[216:217], v[188:189]
	v_pk_fma_f32 v[190:191], v[198:199], v[218:219], v[190:191]
	v_pk_fma_f32 v[234:235], v[188:189], v[188:189], v[234:235]
	v_pk_fma_f32 v[234:235], v[190:191], v[190:191], v[234:235]
	v_lshlrev_b32_e32 v212, 16, v2
	v_and_b32_e32 v213, 0xffff0000, v2
	v_lshlrev_b32_e32 v214, 16, v3
	v_and_b32_e32 v215, 0xffff0000, v3
	v_lshlrev_b32_e32 v216, 16, v4
	v_and_b32_e32 v217, 0xffff0000, v4
	v_lshlrev_b32_e32 v218, 16, v5
	v_and_b32_e32 v219, 0xffff0000, v5
	v_pk_mul_f32 v[212:213], v[228:229], v[212:213]
	v_pk_mul_f32 v[214:215], v[228:229], v[214:215]
	v_pk_mul_f32 v[216:217], v[230:231], v[216:217]
	v_pk_mul_f32 v[218:219], v[230:231], v[218:219]
	s_waitcnt lgkmcnt(0)
	v_pk_mul_f32 v[192:193], v[212:213], v[208:209]
	v_pk_mul_f32 v[194:195], v[214:215], v[210:211]
	v_pk_fma_f32 v[192:193], v[204:205], v[216:217], v[192:193]
	v_pk_fma_f32 v[194:195], v[206:207], v[218:219], v[194:195]
	v_pk_fma_f32 v[234:235], v[192:193], v[192:193], v[234:235]
	v_pk_fma_f32 v[234:235], v[194:195], v[194:195], v[234:235]
	v_add_f32_e32 v77, v234, v235
	ds_bpermute_b32 v70, v70, v77
	s_waitcnt lgkmcnt(0)
	v_add_f32_e32 v70, v77, v70
	ds_bpermute_b32 v72, v72, v70
	s_waitcnt lgkmcnt(0)
	v_add_f32_e32 v70, v70, v72
	ds_bpermute_b32 v72, v73, v70
	s_waitcnt lgkmcnt(0)
	v_add_f32_e32 v70, v70, v72
	ds_bpermute_b32 v72, v74, v70
	s_waitcnt lgkmcnt(0)
	v_add_f32_e32 v70, v70, v72
	ds_bpermute_b32 v72, v75, v70
	s_waitcnt lgkmcnt(0)
	v_add_f32_e32 v70, v70, v72
	ds_bpermute_b32 v72, v76, v70
	s_waitcnt lgkmcnt(0)
	v_add_f32_e32 v70, v70, v72
	v_fmamk_f32 v70, v70, 0x39800000, v100
	v_mul_f32_e32 v72, 0x4b800000, v70
	v_cmp_gt_f32_e32 vcc, s66, v70
	s_nop 1
	v_cndmask_b32_e32 v70, v70, v72, vcc
	v_rsq_f32_e32 v70, v70
	s_nop 0
	v_mul_f32_e32 v72, 0x45800000, v70
	v_cndmask_b32_e32 v70, v70, v72, vcc
	s_and_saveexec_b64 s[6:7], s[4:5]
	s_cbranch_execz .LBB0_1118
	global_store_dword v79, v70, s[62:63]
	s_branch .LBB0_1118
